# FFN-up sample epilogue: 375 zero-init + DPP shift pairs fused into bound_ctrl DPP moves (295 place-holder nops dropped)
# speedup vs baseline: 1.0070x; 1.0070x over previous
;     __device__ __forceinline__ f32x4 conv4s(const f32x4 c4, const f32x4 pv, int t, const f32x4 w0, const f32x4 w1, const f32x4 w2, const f32x4 bsv) const {
;         f32x4 p1, p2;
; #pragma unroll
;         for (int e = 0; e < 4; ++e) { p1[e] = dpp_f<0x111>(0.f, c4[e]); p2[e] = dpp_f<0x112>(0.f, c4[e]); const float q1 = dpp_f<0x101>(0.f, pv[e]);
;             p1[e] = t == 0 ? q1 : p1[e]; p2[e] = t < 2 ? pv[e] : p2[e]; }
;         f32x4 uu = bsv + w2 * c4 + w1 * p1 + w0 * p2;
;         asm volatile("" : "+v"(uu));
;         return uu;
;     __device__ __forceinline__ void sample(f32x4 (&acc)[2][2][4][2], const Unit& u, int row0t, int wr, int wc, int fr, int fq) const {
;     ...
; #pragma unroll
;         for (int n = 0; n < 2; ++n) {
;             const unsigned cso = (unsigned)((ca + 4 * n) * 4);
;             const f32x4 w0 = *(const f32x4*)((const char*)cw + cso), w1 = *(const f32x4*)((const char*)(cw + DFF2) + cso), w2 = *(const f32x4*)((const char*)(cw + 2 * DFF2) + cso), bsv = *(const f32x4*)((const char*)cb + cso);
; #pragma unroll
;             for (int ai = 0; ai < 2; ++ai) {
; #pragma unroll
;                 for (int mp = 0; mp < 4; mp += 4) {
;                     f32x4 pv[4];
; #pragma unroll
;                     for (int k = 0; k < 4; ++k) { pv[k] = (f32x4){0.f, 0.f, 0.f, 0.f}; if (t < 2) pv[k] = *(const f32x4*)((const char*)st + stoff + (unsigned)(((16 * ai + 2 * (mp + k)) * 2 * DFF2 + 4 * n) * 4)); }
; #pragma unroll
;                     for (int k = 0; k < 4; ++k) acc[ai][0][mp + k][n] = conv4s(acc[ai][0][mp + k][n], pv[k], t, w0, w1, w2, bsv);
;                     __builtin_amdgcn_sched_barrier(0);
;                 }
.Lspp_0:
	s_or_b64 exec, exec, s[100:101]
	s_nop 4
	v_mov_b32_e32 v37, 0
	v_mov_b32_e32 v38, 0
	v_mov_b32_e32 v39, 0
	v_mov_b32_e32 v28, 0
	v_mov_b32_e32 v40, 0
	v_mov_b32_e32 v41, 0
	v_mov_b32_e32 v42, 0
	v_mov_b32_e32 v43, 0
	v_mov_b32_e32 v29, 0
	v_mov_b32_e32 v30, 0
	v_mov_b32_e32 v31, 0
	s_nop 0
	s_nop 0
	v_mov_b32_e32 v110, v19
	v_mov_b32_dpp v18, v168 row_shr:1 row_mask:0xf bank_mask:0xf bound_ctrl:1
	v_mov_b32_dpp v109, v168 row_shr:2 row_mask:0xf bank_mask:0xf bound_ctrl:1
	s_waitcnt vmcnt(0)
	v_mov_b32_e32 v204, 0
	v_mov_b32_e32 v205, 0
	v_mov_b32_e32 v206, 0
	v_mov_b32_e32 v207, 0
	v_mov_b32_e32 v208, 0
	v_mov_b32_e32 v209, 0
	v_mov_b32_e32 v210, 0
	v_mov_b32_e32 v211, 0
	v_mov_b32_e32 v212, 0
	v_mov_b32_e32 v213, 0
	v_mov_b32_e32 v214, 0
	v_mov_b32_e32 v215, 0
	v_mov_b32_e32 v216, 0
	v_mov_b32_e32 v217, 0
	v_mov_b32_e32 v218, 0
	v_mov_b32_e32 v219, 0
	s_and_saveexec_b64 s[100:101], s[4:5]
	s_cbranch_execz .Lspp_1
	s_mov_b64 s[98:99], 0xb0000
	v_lshl_add_u64 v[194:195], v[172:173], 0, s[98:99]
	global_load_dwordx4 v[204:207], v[194:195], off
	s_mov_b64 s[98:99], 0xc6000
	v_lshl_add_u64 v[194:195], v[172:173], 0, s[98:99]
	global_load_dwordx4 v[208:211], v[194:195], off
	s_mov_b64 s[98:99], 0xdc000
	v_lshl_add_u64 v[194:195], v[172:173], 0, s[98:99]
	global_load_dwordx4 v[212:215], v[194:195], off
	s_mov_b64 s[98:99], 0xf2000
	v_lshl_add_u64 v[194:195], v[172:173], 0, s[98:99]
	global_load_dwordx4 v[216:219], v[194:195], off
.Lspp_1:
	s_or_b64 exec, exec, s[100:101]
	s_nop 4
	v_mov_b32_dpp v110, v178 row_shl:1 row_mask:0xf bank_mask:0xf
	v_cmp_eq_u32_e64 s[6:7], 0, v108
	v_cndmask_b32_e64 v100, v109, v178, s[4:5]
	s_nop 0
	v_cndmask_b32_e64 v108, v18, v110, s[6:7]
	s_nop 0
	s_nop 0
	v_mov_b32_dpp v109, v179 row_shl:1 row_mask:0xf bank_mask:0xf bound_ctrl:1
	v_mov_b32_dpp v18, v169 row_shr:1 row_mask:0xf bank_mask:0xf bound_ctrl:1
	v_mov_b32_dpp v110, v169 row_shr:2 row_mask:0xf bank_mask:0xf bound_ctrl:1
	v_cndmask_b32_e64 v109, v18, v109, s[6:7]
	v_cndmask_b32_e64 v101, v110, v179, s[4:5]
	v_mov_b32_dpp v18, v170 row_shr:1 row_mask:0xf bank_mask:0xf bound_ctrl:1
	v_mov_b32_dpp v111, v170 row_shr:2 row_mask:0xf bank_mask:0xf bound_ctrl:1
	v_mov_b32_dpp v110, v180 row_shl:1 row_mask:0xf bank_mask:0xf bound_ctrl:1
	v_cndmask_b32_e64 v110, v18, v110, s[6:7]
	v_cndmask_b32_e64 v102, v111, v180, s[4:5]
	v_mov_b32_dpp v18, v171 row_shr:1 row_mask:0xf bank_mask:0xf bound_ctrl:1
	v_mov_b32_dpp v112, v171 row_shr:2 row_mask:0xf bank_mask:0xf bound_ctrl:1
	v_mov_b32_dpp v111, v181 row_shl:1 row_mask:0xf bank_mask:0xf bound_ctrl:1
	v_pk_fma_f32 v[114:115], v[168:169], v[156:157], v[160:161]
	v_cndmask_b32_e64 v111, v18, v111, s[6:7]
	v_cndmask_b32_e64 v103, v112, v181, s[4:5]
	v_pk_fma_f32 v[112:113], v[170:171], v[158:159], v[162:163]
	v_pk_fma_f32 v[108:109], v[152:153], v[108:109], v[114:115]
	v_pk_fma_f32 v[110:111], v[154:155], v[110:111], v[112:113]
	v_pk_fma_f32 v[112:113], v[24:25], v[100:101], v[108:109]
	v_mov_b32_dpp v18, v164 row_shr:1 row_mask:0xf bank_mask:0xf bound_ctrl:1
	v_mov_b32_dpp v101, v164 row_shr:2 row_mask:0xf bank_mask:0xf bound_ctrl:1
	v_mov_b32_dpp v100, v182 row_shl:1 row_mask:0xf bank_mask:0xf bound_ctrl:1
	v_pk_fma_f32 v[114:115], v[26:27], v[102:103], v[110:111]
	v_cndmask_b32_e64 v100, v18, v100, s[6:7]
	v_cndmask_b32_e64 v36, v101, v182, s[4:5]
	v_mov_b32_dpp v18, v165 row_shr:1 row_mask:0xf bank_mask:0xf bound_ctrl:1
	v_mov_b32_dpp v102, v165 row_shr:2 row_mask:0xf bank_mask:0xf bound_ctrl:1
	v_mov_b32_dpp v101, v183 row_shl:1 row_mask:0xf bank_mask:0xf bound_ctrl:1
	v_cndmask_b32_e64 v101, v18, v101, s[6:7]
	v_cndmask_b32_e64 v37, v102, v183, s[4:5]
	v_mov_b32_dpp v18, v166 row_shr:1 row_mask:0xf bank_mask:0xf bound_ctrl:1
	v_mov_b32_dpp v103, v166 row_shr:2 row_mask:0xf bank_mask:0xf bound_ctrl:1
	v_mov_b32_dpp v102, v184 row_shl:1 row_mask:0xf bank_mask:0xf bound_ctrl:1
	v_cndmask_b32_e64 v102, v18, v102, s[6:7]
	v_cndmask_b32_e64 v38, v103, v184, s[4:5]
	v_mov_b32_dpp v18, v167 row_shr:1 row_mask:0xf bank_mask:0xf bound_ctrl:1
	v_mov_b32_dpp v108, v167 row_shr:2 row_mask:0xf bank_mask:0xf bound_ctrl:1
	v_mov_b32_dpp v103, v185 row_shl:1 row_mask:0xf bank_mask:0xf bound_ctrl:1
	v_pk_fma_f32 v[110:111], v[164:165], v[156:157], v[160:161]
	v_cndmask_b32_e64 v103, v18, v103, s[6:7]
	v_cndmask_b32_e64 v39, v108, v185, s[4:5]
	v_pk_fma_f32 v[108:109], v[166:167], v[158:159], v[162:163]
	v_pk_fma_f32 v[100:101], v[152:153], v[100:101], v[110:111]
	v_pk_fma_f32 v[102:103], v[154:155], v[102:103], v[108:109]
	v_pk_fma_f32 v[108:109], v[24:25], v[36:37], v[100:101]
	v_mov_b32_dpp v18, v104 row_shr:1 row_mask:0xf bank_mask:0xf bound_ctrl:1
	v_mov_b32_dpp v37, v104 row_shr:2 row_mask:0xf bank_mask:0xf bound_ctrl:1
	v_mov_b32_dpp v36, v186 row_shl:1 row_mask:0xf bank_mask:0xf bound_ctrl:1
	v_pk_fma_f32 v[110:111], v[26:27], v[38:39], v[102:103]
	v_cndmask_b32_e64 v36, v18, v36, s[6:7]
	v_cndmask_b32_e64 v38, v37, v186, s[4:5]
	v_mov_b32_dpp v18, v105 row_shr:1 row_mask:0xf bank_mask:0xf bound_ctrl:1
	v_mov_b32_dpp v39, v105 row_shr:2 row_mask:0xf bank_mask:0xf bound_ctrl:1
	v_mov_b32_dpp v37, v187 row_shl:1 row_mask:0xf bank_mask:0xf bound_ctrl:1
	v_cndmask_b32_e64 v37, v18, v37, s[6:7]
	v_cndmask_b32_e64 v39, v39, v187, s[4:5]
	v_mov_b32_dpp v18, v106 row_shr:1 row_mask:0xf bank_mask:0xf bound_ctrl:1
	v_mov_b32_dpp v41, v106 row_shr:2 row_mask:0xf bank_mask:0xf bound_ctrl:1
	v_mov_b32_dpp v40, v188 row_shl:1 row_mask:0xf bank_mask:0xf bound_ctrl:1
	v_cndmask_b32_e64 v40, v18, v40, s[6:7]
	v_cndmask_b32_e64 v42, v41, v188, s[4:5]
	v_pk_fma_f32 v[102:103], v[104:105], v[156:157], v[160:161]
;     __device__ __forceinline__ f32x4 conv4s(const f32x4 c4, const f32x4 pv, int t, const f32x4 w0, const f32x4 w1, const f32x4 w2, const f32x4 bsv) const {
;         f32x4 p1, p2;
; #pragma unroll
;         for (int e = 0; e < 4; ++e) { p1[e] = dpp_f<0x111>(0.f, c4[e]); p2[e] = dpp_f<0x112>(0.f, c4[e]); const float q1 = dpp_f<0x101>(0.f, pv[e]);
;             p1[e] = t == 0 ? q1 : p1[e]; p2[e] = t < 2 ? pv[e] : p2[e]; }
;         f32x4 uu = bsv + w2 * c4 + w1 * p1 + w0 * p2;
;         asm volatile("" : "+v"(uu));
;         return uu;
;     __device__ __forceinline__ void sample(f32x4 (&acc)[2][2][4][2], const Unit& u, int row0t, int wr, int wc, int fr, int fq) const {
;     ...
; #pragma unroll
;         for (int n = 0; n < 2; ++n) {
;             const unsigned cso = (unsigned)((ca + 4 * n) * 4);
;             const f32x4 w0 = *(const f32x4*)((const char*)cw + cso), w1 = *(const f32x4*)((const char*)(cw + DFF2) + cso), w2 = *(const f32x4*)((const char*)(cw + 2 * DFF2) + cso), bsv = *(const f32x4*)((const char*)cb + cso);
; #pragma unroll
;             for (int ai = 0; ai < 2; ++ai) {
; #pragma unroll
;                 for (int mp = 0; mp < 4; mp += 4) {
;                     f32x4 pv[4];
; #pragma unroll
;                     for (int k = 0; k < 4; ++k) { pv[k] = (f32x4){0.f, 0.f, 0.f, 0.f}; if (t < 2) pv[k] = *(const f32x4*)((const char*)st + stoff + (unsigned)(((16 * ai + 2 * (mp + k)) * 2 * DFF2 + 4 * n) * 4)); }
; #pragma unroll
;                     for (int k = 0; k < 4; ++k) acc[ai][0][mp + k][n] = conv4s(acc[ai][0][mp + k][n], pv[k], t, w0, w1, w2, bsv);
;                     __builtin_amdgcn_sched_barrier(0);
;                 }
	v_mov_b32_dpp v18, v107 row_shr:1 row_mask:0xf bank_mask:0xf bound_ctrl:1
	v_mov_b32_dpp v41, v189 row_shl:1 row_mask:0xf bank_mask:0xf bound_ctrl:1
	v_pk_fma_f32 v[36:37], v[152:153], v[36:37], v[102:103]
	v_cndmask_b32_e64 v41, v18, v41, s[6:7]
	v_pk_fma_f32 v[104:105], v[24:25], v[38:39], v[36:37]
	v_mov_b32_dpp v18, v136 row_shr:1 row_mask:0xf bank_mask:0xf bound_ctrl:1
	v_mov_b32_dpp v37, v136 row_shr:2 row_mask:0xf bank_mask:0xf bound_ctrl:1
	v_mov_b32_dpp v36, v190 row_shl:1 row_mask:0xf bank_mask:0xf bound_ctrl:1
	v_cndmask_b32_e64 v36, v18, v36, s[6:7]
	v_cndmask_b32_e64 v28, v37, v190, s[4:5]
	v_mov_b32_dpp v100, v107 row_shr:2 row_mask:0xf bank_mask:0xf bound_ctrl:1
	v_mov_b32_dpp v18, v137 row_shr:1 row_mask:0xf bank_mask:0xf bound_ctrl:1
	v_mov_b32_dpp v38, v137 row_shr:2 row_mask:0xf bank_mask:0xf bound_ctrl:1
	v_mov_b32_dpp v37, v191 row_shl:1 row_mask:0xf bank_mask:0xf bound_ctrl:1
	v_cndmask_b32_e64 v43, v100, v189, s[4:5]
	v_pk_fma_f32 v[100:101], v[106:107], v[158:159], v[162:163]
	v_cndmask_b32_e64 v37, v18, v37, s[6:7]
	v_cndmask_b32_e64 v29, v38, v191, s[4:5]
	v_pk_fma_f32 v[40:41], v[154:155], v[40:41], v[100:101]
	v_mov_b32_dpp v18, v138 row_shr:1 row_mask:0xf bank_mask:0xf bound_ctrl:1
	v_mov_b32_dpp v39, v138 row_shr:2 row_mask:0xf bank_mask:0xf bound_ctrl:1
	v_mov_b32_dpp v38, v192 row_shl:1 row_mask:0xf bank_mask:0xf bound_ctrl:1
	v_pk_fma_f32 v[106:107], v[26:27], v[42:43], v[40:41]
	v_cndmask_b32_e64 v38, v18, v38, s[6:7]
	v_cndmask_b32_e64 v30, v39, v192, s[4:5]
	v_mov_b32_dpp v18, v139 row_shr:1 row_mask:0xf bank_mask:0xf bound_ctrl:1
	v_mov_b32_dpp v40, v139 row_shr:2 row_mask:0xf bank_mask:0xf bound_ctrl:1
	v_mov_b32_dpp v39, v193 row_shl:1 row_mask:0xf bank_mask:0xf bound_ctrl:1
	v_cndmask_b32_e64 v39, v18, v39, s[6:7]
	v_cndmask_b32_e64 v31, v40, v193, s[4:5]
	v_pk_fma_f32 v[40:41], v[138:139], v[158:159], v[162:163]
	v_pk_fma_f32 v[42:43], v[136:137], v[156:157], v[160:161]
	v_pk_fma_f32 v[38:39], v[154:155], v[38:39], v[40:41]
	v_pk_fma_f32 v[36:37], v[152:153], v[36:37], v[42:43]
	v_pk_fma_f32 v[102:103], v[26:27], v[30:31], v[38:39]
	v_pk_fma_f32 v[100:101], v[24:25], v[28:29], v[36:37]
	s_nop 0
	v_mov_b32_e32 v28, 0
	v_mov_b32_e32 v36, 0
	v_mov_b32_e32 v37, 0
	v_mov_b32_e32 v38, 0
	v_mov_b32_e32 v39, 0
	v_mov_b32_e32 v29, 0
	v_mov_b32_e32 v30, 0
	v_mov_b32_e32 v31, 0
	v_mov_b32_e32 v136, 0
	v_mov_b32_e32 v164, 0
	v_mov_b32_e32 v165, 0
	v_mov_b32_e32 v166, 0
	v_mov_b32_e32 v167, 0
	v_mov_b32_e32 v137, 0
	v_mov_b32_e32 v138, 0
	v_mov_b32_e32 v139, 0
	s_nop 0
	s_nop 0
	v_mov_b32_e32 v40, v19
	v_mov_b32_dpp v18, v148 row_shr:1 row_mask:0xf bank_mask:0xf bound_ctrl:1
	v_mov_b32_dpp v41, v148 row_shr:2 row_mask:0xf bank_mask:0xf bound_ctrl:1
	s_waitcnt vmcnt(0)
	v_mov_b32_e32 v178, 0
	v_mov_b32_e32 v179, 0
	v_mov_b32_e32 v180, 0
	v_mov_b32_e32 v181, 0
	v_mov_b32_e32 v182, 0
	v_mov_b32_e32 v183, 0
	v_mov_b32_e32 v184, 0
	v_mov_b32_e32 v185, 0
	v_mov_b32_e32 v186, 0
	v_mov_b32_e32 v187, 0
	v_mov_b32_e32 v188, 0
	v_mov_b32_e32 v189, 0
	v_mov_b32_e32 v190, 0
	v_mov_b32_e32 v191, 0
	v_mov_b32_e32 v192, 0
	v_mov_b32_e32 v193, 0
	s_and_saveexec_b64 s[100:101], s[4:5]
	s_cbranch_execz .Lspp_2
	s_mov_b64 s[98:99], 0x10
	v_lshl_add_u64 v[194:195], v[172:173], 0, s[98:99]
	global_load_dwordx4 v[178:181], v[194:195], off
	s_mov_b64 s[98:99], 0x16010
	v_lshl_add_u64 v[194:195], v[172:173], 0, s[98:99]
	global_load_dwordx4 v[182:185], v[194:195], off
	s_mov_b64 s[98:99], 0x2c010
	v_lshl_add_u64 v[194:195], v[172:173], 0, s[98:99]
	global_load_dwordx4 v[186:189], v[194:195], off
	s_mov_b64 s[98:99], 0x42010
	v_lshl_add_u64 v[194:195], v[172:173], 0, s[98:99]
	global_load_dwordx4 v[190:193], v[194:195], off
.Lspp_2:
	s_or_b64 exec, exec, s[100:101]
	s_nop 4
	v_mov_b32_dpp v40, v204 row_shl:1 row_mask:0xf bank_mask:0xf
	v_cndmask_b32_e64 v40, v18, v40, s[6:7]
	v_cndmask_b32_e64 v36, v41, v204, s[4:5]
	s_nop 0
	s_nop 0
	v_mov_b32_dpp v18, v149 row_shr:1 row_mask:0xf bank_mask:0xf bound_ctrl:1
	v_mov_b32_dpp v42, v149 row_shr:2 row_mask:0xf bank_mask:0xf bound_ctrl:1
	v_mov_b32_dpp v41, v205 row_shl:1 row_mask:0xf bank_mask:0xf bound_ctrl:1
	v_cndmask_b32_e64 v41, v18, v41, s[6:7]
	v_cndmask_b32_e64 v37, v42, v205, s[4:5]
	v_mov_b32_dpp v18, v150 row_shr:1 row_mask:0xf bank_mask:0xf bound_ctrl:1
	v_mov_b32_dpp v43, v150 row_shr:2 row_mask:0xf bank_mask:0xf bound_ctrl:1
	v_mov_b32_dpp v42, v206 row_shl:1 row_mask:0xf bank_mask:0xf bound_ctrl:1
	v_cndmask_b32_e64 v42, v18, v42, s[6:7]
	v_cndmask_b32_e64 v38, v43, v206, s[4:5]
	v_pk_fma_f32 v[148:149], v[148:149], v[156:157], v[160:161]
	v_mov_b32_dpp v18, v151 row_shr:1 row_mask:0xf bank_mask:0xf bound_ctrl:1
	v_mov_b32_dpp v43, v207 row_shl:1 row_mask:0xf bank_mask:0xf bound_ctrl:1
	v_pk_fma_f32 v[40:41], v[152:153], v[40:41], v[148:149]
	v_mov_b32_dpp v168, v151 row_shr:2 row_mask:0xf bank_mask:0xf bound_ctrl:1
	v_cndmask_b32_e64 v43, v18, v43, s[6:7]
	v_pk_fma_f32 v[150:151], v[150:151], v[158:159], v[162:163]
	v_pk_fma_f32 v[40:41], v[24:25], v[36:37], v[40:41]
	v_cndmask_b32_e64 v39, v168, v207, s[4:5]
	v_pk_fma_f32 v[42:43], v[154:155], v[42:43], v[150:151]
	v_mov_b32_dpp v18, v144 row_shr:1 row_mask:0xf bank_mask:0xf bound_ctrl:1
	v_mov_b32_dpp v37, v144 row_shr:2 row_mask:0xf bank_mask:0xf bound_ctrl:1
	v_mov_b32_dpp v36, v208 row_shl:1 row_mask:0xf bank_mask:0xf bound_ctrl:1
	v_pk_fma_f32 v[42:43], v[26:27], v[38:39], v[42:43]
	v_cndmask_b32_e64 v36, v18, v36, s[6:7]
	v_cndmask_b32_e64 v28, v37, v208, s[4:5]
	v_mov_b32_dpp v18, v145 row_shr:1 row_mask:0xf bank_mask:0xf bound_ctrl:1
	v_mov_b32_dpp v38, v145 row_shr:2 row_mask:0xf bank_mask:0xf bound_ctrl:1
;     __device__ __forceinline__ void sample(f32x4 (&acc)[2][2][4][2], const Unit& u, int row0t, int wr, int wc, int fr, int fq) const {
;     ...
; #pragma unroll
;         for (int n = 0; n < 2; ++n) {
;             const unsigned cso = (unsigned)((ca + 4 * n) * 4);
;             const f32x4 w0 = *(const f32x4*)((const char*)cw + cso), w1 = *(const f32x4*)((const char*)(cw + DFF2) + cso), w2 = *(const f32x4*)((const char*)(cw + 2 * DFF2) + cso), bsv = *(const f32x4*)((const char*)cb + cso);
; #pragma unroll
;             for (int ai = 0; ai < 2; ++ai) {
; #pragma unroll
;                 for (int mp = 0; mp < 4; mp += 4) {
;                     f32x4 pv[4];
; #pragma unroll
;                     for (int k = 0; k < 4; ++k) { pv[k] = (f32x4){0.f, 0.f, 0.f, 0.f}; if (t < 2) pv[k] = *(const f32x4*)((const char*)st + stoff + (unsigned)(((16 * ai + 2 * (mp + k)) * 2 * DFF2 + 4 * n) * 4)); }
; #pragma unroll
;                     for (int k = 0; k < 4; ++k) acc[ai][0][mp + k][n] = conv4s(acc[ai][0][mp + k][n], pv[k], t, w0, w1, w2, bsv);
;                     __builtin_amdgcn_sched_barrier(0);
;                 }
	v_mov_b32_dpp v37, v209 row_shl:1 row_mask:0xf bank_mask:0xf bound_ctrl:1
	v_cndmask_b32_e64 v37, v18, v37, s[6:7]
	v_cndmask_b32_e64 v29, v38, v209, s[4:5]
	v_mov_b32_dpp v18, v146 row_shr:1 row_mask:0xf bank_mask:0xf bound_ctrl:1
	v_mov_b32_dpp v39, v146 row_shr:2 row_mask:0xf bank_mask:0xf bound_ctrl:1
	v_mov_b32_dpp v38, v210 row_shl:1 row_mask:0xf bank_mask:0xf bound_ctrl:1
	v_cndmask_b32_e64 v38, v18, v38, s[6:7]
	v_cndmask_b32_e64 v30, v39, v210, s[4:5]
	v_pk_fma_f32 v[144:145], v[144:145], v[156:157], v[160:161]
	v_mov_b32_dpp v18, v147 row_shr:1 row_mask:0xf bank_mask:0xf bound_ctrl:1
	v_mov_b32_dpp v39, v211 row_shl:1 row_mask:0xf bank_mask:0xf bound_ctrl:1
	v_pk_fma_f32 v[36:37], v[152:153], v[36:37], v[144:145]
	v_mov_b32_dpp v148, v147 row_shr:2 row_mask:0xf bank_mask:0xf bound_ctrl:1
	v_cndmask_b32_e64 v39, v18, v39, s[6:7]
	v_pk_fma_f32 v[146:147], v[146:147], v[158:159], v[162:163]
	v_pk_fma_f32 v[36:37], v[24:25], v[28:29], v[36:37]
	v_cndmask_b32_e64 v31, v148, v211, s[4:5]
	v_pk_fma_f32 v[38:39], v[154:155], v[38:39], v[146:147]
	v_mov_b32_dpp v18, v140 row_shr:1 row_mask:0xf bank_mask:0xf bound_ctrl:1
	v_mov_b32_dpp v29, v140 row_shr:2 row_mask:0xf bank_mask:0xf bound_ctrl:1
	v_mov_b32_dpp v28, v212 row_shl:1 row_mask:0xf bank_mask:0xf bound_ctrl:1
	v_pk_fma_f32 v[38:39], v[26:27], v[30:31], v[38:39]
	v_cndmask_b32_e64 v28, v18, v28, s[6:7]
	v_cndmask_b32_e64 v144, v29, v212, s[4:5]
	v_mov_b32_dpp v18, v141 row_shr:1 row_mask:0xf bank_mask:0xf bound_ctrl:1
	v_mov_b32_dpp v30, v141 row_shr:2 row_mask:0xf bank_mask:0xf bound_ctrl:1
	v_mov_b32_dpp v29, v213 row_shl:1 row_mask:0xf bank_mask:0xf bound_ctrl:1
	v_cndmask_b32_e64 v29, v18, v29, s[6:7]
	v_cndmask_b32_e64 v145, v30, v213, s[4:5]
	v_mov_b32_dpp v18, v142 row_shr:1 row_mask:0xf bank_mask:0xf bound_ctrl:1
	v_mov_b32_dpp v31, v142 row_shr:2 row_mask:0xf bank_mask:0xf bound_ctrl:1
	v_mov_b32_dpp v30, v214 row_shl:1 row_mask:0xf bank_mask:0xf bound_ctrl:1
	v_cndmask_b32_e64 v30, v18, v30, s[6:7]
	v_cndmask_b32_e64 v146, v31, v214, s[4:5]
	v_pk_fma_f32 v[140:141], v[140:141], v[156:157], v[160:161]
	v_mov_b32_dpp v18, v143 row_shr:1 row_mask:0xf bank_mask:0xf bound_ctrl:1
	v_mov_b32_dpp v31, v215 row_shl:1 row_mask:0xf bank_mask:0xf bound_ctrl:1
	v_cndmask_b32_e64 v31, v18, v31, s[6:7]
	v_pk_fma_f32 v[28:29], v[152:153], v[28:29], v[140:141]
	v_mov_b32_dpp v147, v143 row_shr:2 row_mask:0xf bank_mask:0xf bound_ctrl:1
	v_pk_fma_f32 v[142:143], v[142:143], v[158:159], v[162:163]
	v_mov_b32_dpp v18, v128 row_shr:1 row_mask:0xf bank_mask:0xf bound_ctrl:1
	v_mov_b32_dpp v141, v128 row_shr:2 row_mask:0xf bank_mask:0xf bound_ctrl:1
	v_mov_b32_dpp v140, v216 row_shl:1 row_mask:0xf bank_mask:0xf bound_ctrl:1
	v_pk_fma_f32 v[30:31], v[154:155], v[30:31], v[142:143]
	v_cndmask_b32_e64 v140, v18, v140, s[6:7]
	v_cndmask_b32_e64 v136, v141, v216, s[4:5]
	v_mov_b32_dpp v18, v129 row_shr:1 row_mask:0xf bank_mask:0xf bound_ctrl:1
	v_mov_b32_dpp v142, v129 row_shr:2 row_mask:0xf bank_mask:0xf bound_ctrl:1
	v_mov_b32_dpp v141, v217 row_shl:1 row_mask:0xf bank_mask:0xf bound_ctrl:1
	v_cndmask_b32_e64 v141, v18, v141, s[6:7]
	v_cndmask_b32_e64 v137, v142, v217, s[4:5]
	v_mov_b32_dpp v18, v130 row_shr:1 row_mask:0xf bank_mask:0xf bound_ctrl:1
	v_mov_b32_dpp v143, v130 row_shr:2 row_mask:0xf bank_mask:0xf bound_ctrl:1
	v_mov_b32_dpp v142, v218 row_shl:1 row_mask:0xf bank_mask:0xf bound_ctrl:1
	v_cndmask_b32_e64 v142, v18, v142, s[6:7]
	v_cndmask_b32_e64 v138, v143, v218, s[4:5]
	v_pk_fma_f32 v[28:29], v[24:25], v[144:145], v[28:29]
	v_mov_b32_dpp v18, v131 row_shr:1 row_mask:0xf bank_mask:0xf bound_ctrl:1
	v_mov_b32_dpp v143, v219 row_shl:1 row_mask:0xf bank_mask:0xf bound_ctrl:1
	v_cndmask_b32_e64 v143, v18, v143, s[6:7]
	v_mov_b32_dpp v144, v131 row_shr:2 row_mask:0xf bank_mask:0xf bound_ctrl:1
	v_pk_fma_f32 v[130:131], v[130:131], v[158:159], v[162:163]
	v_pk_fma_f32 v[128:129], v[128:129], v[156:157], v[160:161]
	v_cndmask_b32_e64 v147, v147, v215, s[4:5]
	v_cndmask_b32_e64 v139, v144, v219, s[4:5]
	v_pk_fma_f32 v[130:131], v[154:155], v[142:143], v[130:131]
	v_pk_fma_f32 v[128:129], v[152:153], v[140:141], v[128:129]
	v_pk_fma_f32 v[30:31], v[26:27], v[146:147], v[30:31]
	v_pk_fma_f32 v[26:27], v[26:27], v[138:139], v[130:131]
	v_pk_fma_f32 v[24:25], v[24:25], v[136:137], v[128:129]
	s_nop 0
	v_add_u32_e32 v18, 16, v176
	global_load_dwordx4 v[140:143], v18, s[0:1]
	global_load_dwordx4 v[144:147], v18, s[8:9]
	global_load_dwordx4 v[136:139], v18, s[96:97]
	global_load_dwordx4 v[148:151], v18, s[66:67]
	v_mov_b32_e32 v156, 0
	v_mov_b32_e32 v128, 0
	v_mov_b32_e32 v129, 0
	v_mov_b32_e32 v130, 0
	v_mov_b32_e32 v131, 0
	v_mov_b32_e32 v157, 0
	v_mov_b32_e32 v158, 0
	v_mov_b32_e32 v159, 0
	v_mov_b32_e32 v152, 0
	v_mov_b32_e32 v160, 0
	v_mov_b32_e32 v161, 0
	v_mov_b32_e32 v162, 0
	v_mov_b32_e32 v163, 0
	v_mov_b32_e32 v153, 0
	v_mov_b32_e32 v154, 0
	v_mov_b32_e32 v155, 0
	s_nop 0
	s_nop 0
	v_mov_b32_e32 v164, v19
	v_mov_b32_dpp v18, v124 row_shr:1 row_mask:0xf bank_mask:0xf bound_ctrl:1
	v_mov_b32_dpp v165, v124 row_shr:2 row_mask:0xf bank_mask:0xf bound_ctrl:1
	s_waitcnt vmcnt(0)
	v_mov_b32_e32 v204, 0
	v_mov_b32_e32 v205, 0
	v_mov_b32_e32 v206, 0
	v_mov_b32_e32 v207, 0
	v_mov_b32_e32 v208, 0
	v_mov_b32_e32 v209, 0
	v_mov_b32_e32 v210, 0
	v_mov_b32_e32 v211, 0
	v_mov_b32_e32 v212, 0
	v_mov_b32_e32 v213, 0
	v_mov_b32_e32 v214, 0
	v_mov_b32_e32 v215, 0
	v_mov_b32_e32 v216, 0
	v_mov_b32_e32 v217, 0
	v_mov_b32_e32 v218, 0
	v_mov_b32_e32 v219, 0
	s_and_saveexec_b64 s[100:101], s[4:5]
	s_cbranch_execz .Lspp_3
	s_mov_b64 s[98:99], 0xb0010
	v_lshl_add_u64 v[194:195], v[172:173], 0, s[98:99]
	global_load_dwordx4 v[204:207], v[194:195], off
	s_mov_b64 s[98:99], 0xc6010
	v_lshl_add_u64 v[194:195], v[172:173], 0, s[98:99]
	global_load_dwordx4 v[208:211], v[194:195], off
	s_mov_b64 s[98:99], 0xdc010
	v_lshl_add_u64 v[194:195], v[172:173], 0, s[98:99]
	global_load_dwordx4 v[212:215], v[194:195], off
	s_mov_b64 s[98:99], 0xf2010
	v_lshl_add_u64 v[194:195], v[172:173], 0, s[98:99]
	global_load_dwordx4 v[216:219], v[194:195], off
;     __device__ __forceinline__ void sample(f32x4 (&acc)[2][2][4][2], const Unit& u, int row0t, int wr, int wc, int fr, int fq) const {
;     ...
; #pragma unroll
;         for (int n = 0; n < 2; ++n) {
;             const unsigned cso = (unsigned)((ca + 4 * n) * 4);
;             const f32x4 w0 = *(const f32x4*)((const char*)cw + cso), w1 = *(const f32x4*)((const char*)(cw + DFF2) + cso), w2 = *(const f32x4*)((const char*)(cw + 2 * DFF2) + cso), bsv = *(const f32x4*)((const char*)cb + cso);
; #pragma unroll
;             for (int ai = 0; ai < 2; ++ai) {
; #pragma unroll
;                 for (int mp = 0; mp < 4; mp += 4) {
;                     f32x4 pv[4];
; #pragma unroll
;                     for (int k = 0; k < 4; ++k) { pv[k] = (f32x4){0.f, 0.f, 0.f, 0.f}; if (t < 2) pv[k] = *(const f32x4*)((const char*)st + stoff + (unsigned)(((16 * ai + 2 * (mp + k)) * 2 * DFF2 + 4 * n) * 4)); }
; #pragma unroll
;                     for (int k = 0; k < 4; ++k) acc[ai][0][mp + k][n] = conv4s(acc[ai][0][mp + k][n], pv[k], t, w0, w1, w2, bsv);
;                     __builtin_amdgcn_sched_barrier(0);
;                 }
.Lspp_3:
	s_or_b64 exec, exec, s[100:101]
	s_nop 4
	v_mov_b32_dpp v164, v178 row_shl:1 row_mask:0xf bank_mask:0xf
	v_cndmask_b32_e64 v164, v18, v164, s[6:7]
	v_cndmask_b32_e64 v128, v165, v178, s[4:5]
	s_nop 0
	s_nop 0
	v_mov_b32_dpp v18, v125 row_shr:1 row_mask:0xf bank_mask:0xf bound_ctrl:1
	v_mov_b32_dpp v166, v125 row_shr:2 row_mask:0xf bank_mask:0xf bound_ctrl:1
	v_mov_b32_dpp v165, v179 row_shl:1 row_mask:0xf bank_mask:0xf bound_ctrl:1
	v_cndmask_b32_e64 v165, v18, v165, s[6:7]
	v_cndmask_b32_e64 v129, v166, v179, s[4:5]
	v_mov_b32_dpp v18, v126 row_shr:1 row_mask:0xf bank_mask:0xf bound_ctrl:1
	v_mov_b32_dpp v167, v126 row_shr:2 row_mask:0xf bank_mask:0xf bound_ctrl:1
	v_mov_b32_dpp v166, v180 row_shl:1 row_mask:0xf bank_mask:0xf bound_ctrl:1
	v_cndmask_b32_e64 v166, v18, v166, s[6:7]
	v_cndmask_b32_e64 v130, v167, v180, s[4:5]
	v_pk_fma_f32 v[124:125], v[124:125], v[144:145], v[148:149]
	v_mov_b32_dpp v18, v127 row_shr:1 row_mask:0xf bank_mask:0xf bound_ctrl:1
	v_mov_b32_dpp v167, v181 row_shl:1 row_mask:0xf bank_mask:0xf bound_ctrl:1
	v_pk_fma_f32 v[124:125], v[140:141], v[164:165], v[124:125]
	v_mov_b32_dpp v168, v127 row_shr:2 row_mask:0xf bank_mask:0xf bound_ctrl:1
	v_cndmask_b32_e64 v167, v18, v167, s[6:7]
	v_pk_fma_f32 v[126:127], v[126:127], v[146:147], v[150:151]
	v_pk_fma_f32 v[128:129], v[136:137], v[128:129], v[124:125]
	v_cndmask_b32_e64 v131, v168, v181, s[4:5]
	v_pk_fma_f32 v[126:127], v[142:143], v[166:167], v[126:127]
	v_mov_b32_dpp v18, v120 row_shr:1 row_mask:0xf bank_mask:0xf bound_ctrl:1
	v_mov_b32_dpp v125, v120 row_shr:2 row_mask:0xf bank_mask:0xf bound_ctrl:1
	v_mov_b32_dpp v124, v182 row_shl:1 row_mask:0xf bank_mask:0xf bound_ctrl:1
	v_pk_fma_f32 v[130:131], v[138:139], v[130:131], v[126:127]
	v_cndmask_b32_e64 v124, v18, v124, s[6:7]
	v_cndmask_b32_e64 v156, v125, v182, s[4:5]
	v_mov_b32_dpp v18, v121 row_shr:1 row_mask:0xf bank_mask:0xf bound_ctrl:1
	v_mov_b32_dpp v126, v121 row_shr:2 row_mask:0xf bank_mask:0xf bound_ctrl:1
	v_mov_b32_dpp v125, v183 row_shl:1 row_mask:0xf bank_mask:0xf bound_ctrl:1
	v_cndmask_b32_e64 v125, v18, v125, s[6:7]
	v_cndmask_b32_e64 v157, v126, v183, s[4:5]
	v_mov_b32_dpp v18, v122 row_shr:1 row_mask:0xf bank_mask:0xf bound_ctrl:1
	v_mov_b32_dpp v127, v122 row_shr:2 row_mask:0xf bank_mask:0xf bound_ctrl:1
	v_mov_b32_dpp v126, v184 row_shl:1 row_mask:0xf bank_mask:0xf bound_ctrl:1
	v_cndmask_b32_e64 v126, v18, v126, s[6:7]
	v_cndmask_b32_e64 v158, v127, v184, s[4:5]
	v_pk_fma_f32 v[120:121], v[120:121], v[144:145], v[148:149]
	v_mov_b32_dpp v18, v123 row_shr:1 row_mask:0xf bank_mask:0xf bound_ctrl:1
	v_mov_b32_dpp v127, v185 row_shl:1 row_mask:0xf bank_mask:0xf bound_ctrl:1
	v_pk_fma_f32 v[120:121], v[140:141], v[124:125], v[120:121]
	v_mov_b32_dpp v164, v123 row_shr:2 row_mask:0xf bank_mask:0xf bound_ctrl:1
	v_cndmask_b32_e64 v127, v18, v127, s[6:7]
	v_pk_fma_f32 v[122:123], v[122:123], v[146:147], v[150:151]
	v_pk_fma_f32 v[124:125], v[136:137], v[156:157], v[120:121]
	v_cndmask_b32_e64 v159, v164, v185, s[4:5]
	v_pk_fma_f32 v[122:123], v[142:143], v[126:127], v[122:123]
	v_mov_b32_dpp v18, v116 row_shr:1 row_mask:0xf bank_mask:0xf bound_ctrl:1
	v_mov_b32_dpp v121, v116 row_shr:2 row_mask:0xf bank_mask:0xf bound_ctrl:1
	v_mov_b32_dpp v120, v186 row_shl:1 row_mask:0xf bank_mask:0xf bound_ctrl:1
	v_pk_fma_f32 v[126:127], v[138:139], v[158:159], v[122:123]
	v_cndmask_b32_e64 v120, v18, v120, s[6:7]
	v_cndmask_b32_e64 v156, v121, v186, s[4:5]
	v_mov_b32_dpp v18, v117 row_shr:1 row_mask:0xf bank_mask:0xf bound_ctrl:1
	v_mov_b32_dpp v122, v117 row_shr:2 row_mask:0xf bank_mask:0xf bound_ctrl:1
	v_mov_b32_dpp v121, v187 row_shl:1 row_mask:0xf bank_mask:0xf bound_ctrl:1
	v_cndmask_b32_e64 v121, v18, v121, s[6:7]
	v_cndmask_b32_e64 v157, v122, v187, s[4:5]
	v_mov_b32_dpp v18, v118 row_shr:1 row_mask:0xf bank_mask:0xf bound_ctrl:1
	v_mov_b32_dpp v123, v118 row_shr:2 row_mask:0xf bank_mask:0xf bound_ctrl:1
	v_mov_b32_dpp v122, v188 row_shl:1 row_mask:0xf bank_mask:0xf bound_ctrl:1
	v_cndmask_b32_e64 v122, v18, v122, s[6:7]
	v_cndmask_b32_e64 v158, v123, v188, s[4:5]
	v_pk_fma_f32 v[116:117], v[116:117], v[144:145], v[148:149]
	v_mov_b32_dpp v18, v119 row_shr:1 row_mask:0xf bank_mask:0xf bound_ctrl:1
	v_mov_b32_dpp v123, v189 row_shl:1 row_mask:0xf bank_mask:0xf bound_ctrl:1
	v_pk_fma_f32 v[116:117], v[140:141], v[120:121], v[116:117]
	v_mov_b32_dpp v159, v119 row_shr:2 row_mask:0xf bank_mask:0xf bound_ctrl:1
	v_cndmask_b32_e64 v123, v18, v123, s[6:7]
	v_pk_fma_f32 v[118:119], v[118:119], v[146:147], v[150:151]
	v_pk_fma_f32 v[120:121], v[136:137], v[156:157], v[116:117]
	v_cndmask_b32_e64 v159, v159, v189, s[4:5]
	v_pk_fma_f32 v[118:119], v[142:143], v[122:123], v[118:119]
	v_mov_b32_dpp v18, v72 row_shr:1 row_mask:0xf bank_mask:0xf bound_ctrl:1
	v_mov_b32_dpp v117, v72 row_shr:2 row_mask:0xf bank_mask:0xf bound_ctrl:1
	v_mov_b32_dpp v116, v190 row_shl:1 row_mask:0xf bank_mask:0xf bound_ctrl:1
	v_pk_fma_f32 v[122:123], v[138:139], v[158:159], v[118:119]
	v_cndmask_b32_e64 v116, v18, v116, s[6:7]
	v_cndmask_b32_e64 v152, v117, v190, s[4:5]
	v_mov_b32_dpp v18, v73 row_shr:1 row_mask:0xf bank_mask:0xf bound_ctrl:1
	v_mov_b32_dpp v118, v73 row_shr:2 row_mask:0xf bank_mask:0xf bound_ctrl:1
	v_mov_b32_dpp v117, v191 row_shl:1 row_mask:0xf bank_mask:0xf bound_ctrl:1
	v_cndmask_b32_e64 v117, v18, v117, s[6:7]
	v_cndmask_b32_e64 v153, v118, v191, s[4:5]
	v_mov_b32_dpp v18, v74 row_shr:1 row_mask:0xf bank_mask:0xf bound_ctrl:1
	v_mov_b32_dpp v119, v74 row_shr:2 row_mask:0xf bank_mask:0xf bound_ctrl:1
	v_mov_b32_dpp v118, v192 row_shl:1 row_mask:0xf bank_mask:0xf bound_ctrl:1
	v_cndmask_b32_e64 v118, v18, v118, s[6:7]
	v_cndmask_b32_e64 v154, v119, v192, s[4:5]
	v_mov_b32_dpp v18, v75 row_shr:1 row_mask:0xf bank_mask:0xf bound_ctrl:1
	v_mov_b32_dpp v119, v193 row_shl:1 row_mask:0xf bank_mask:0xf bound_ctrl:1
	v_mov_b32_dpp v156, v75 row_shr:2 row_mask:0xf bank_mask:0xf bound_ctrl:1
	v_cndmask_b32_e64 v119, v18, v119, s[6:7]
	v_pk_fma_f32 v[74:75], v[74:75], v[146:147], v[150:151]
	v_pk_fma_f32 v[72:73], v[72:73], v[144:145], v[148:149]
	v_cndmask_b32_e64 v155, v156, v193, s[4:5]
	v_pk_fma_f32 v[74:75], v[142:143], v[118:119], v[74:75]
	v_pk_fma_f32 v[72:73], v[140:141], v[116:117], v[72:73]
	v_pk_fma_f32 v[118:119], v[138:139], v[154:155], v[74:75]
	v_pk_fma_f32 v[116:117], v[136:137], v[152:153], v[72:73]
	s_nop 0
	v_mov_b32_e32 v156, 0
	v_mov_b32_e32 v72, 0
	v_mov_b32_e32 v73, 0
	v_mov_b32_e32 v74, 0
	v_mov_b32_e32 v75, 0
	v_mov_b32_e32 v157, 0
	v_mov_b32_e32 v158, 0
	v_mov_b32_e32 v159, 0
	v_mov_b32_e32 v152, 0
	v_mov_b32_e32 v160, 0
	v_mov_b32_e32 v161, 0
	v_mov_b32_e32 v162, 0
	v_mov_b32_e32 v163, 0
	v_mov_b32_e32 v153, 0
	v_mov_b32_e32 v154, 0
	v_mov_b32_e32 v155, 0
	s_nop 0
	s_nop 0
	v_mov_b32_e32 v164, v19
	v_mov_b32_dpp v18, v132 row_shr:1 row_mask:0xf bank_mask:0xf bound_ctrl:1
	v_mov_b32_dpp v165, v132 row_shr:2 row_mask:0xf bank_mask:0xf bound_ctrl:1
	s_waitcnt vmcnt(0)
;     __device__ __forceinline__ void sample(f32x4 (&acc)[2][2][4][2], const Unit& u, int row0t, int wr, int wc, int fr, int fq) const {
;     ...
; #pragma unroll
;         for (int n = 0; n < 2; ++n) {
;             const unsigned cso = (unsigned)((ca + 4 * n) * 4);
;             const f32x4 w0 = *(const f32x4*)((const char*)cw + cso), w1 = *(const f32x4*)((const char*)(cw + DFF2) + cso), w2 = *(const f32x4*)((const char*)(cw + 2 * DFF2) + cso), bsv = *(const f32x4*)((const char*)cb + cso);
; #pragma unroll
;             for (int ai = 0; ai < 2; ++ai) {
; #pragma unroll
;                 for (int mp = 0; mp < 4; mp += 4) {
;                     f32x4 pv[4];
; #pragma unroll
;                     for (int k = 0; k < 4; ++k) { pv[k] = (f32x4){0.f, 0.f, 0.f, 0.f}; if (t < 2) pv[k] = *(const f32x4*)((const char*)st + stoff + (unsigned)(((16 * ai + 2 * (mp + k)) * 2 * DFF2 + 4 * n) * 4)); }
; #pragma unroll
;                     for (int k = 0; k < 4; ++k) acc[ai][0][mp + k][n] = conv4s(acc[ai][0][mp + k][n], pv[k], t, w0, w1, w2, bsv);
;                     __builtin_amdgcn_sched_barrier(0);
;                 }
;     ...
;             for (int mp = 0; mp < 4; mp += 4) {
;             f32x4 pv[4];
; #pragma unroll
;             for (int k = 0; k < 4; ++k) { pv[k] = (f32x4){0.f, 0.f, 0.f, 0.f}; if (t < 2) pv[k] = *(const f32x4*)((const char*)st + stoff + (unsigned)(((16 * ai + 2 * (mp + k)) * 2 * DFF2 + DFF + 4 * n) * 4)); }
; #pragma unroll
;             for (int k = 0; k < 4; ++k) { const int m = mp + k;
;                 const f32x4 uu = conv4s(acc[ai][1][m][n], pv[k], t, w0, w1, w2, bsv);
	v_mov_b32_e32 v178, 0
	v_mov_b32_e32 v179, 0
	v_mov_b32_e32 v180, 0
	v_mov_b32_e32 v181, 0
	v_mov_b32_e32 v182, 0
	v_mov_b32_e32 v183, 0
	v_mov_b32_e32 v184, 0
	v_mov_b32_e32 v185, 0
	v_mov_b32_e32 v186, 0
	v_mov_b32_e32 v187, 0
	v_mov_b32_e32 v188, 0
	v_mov_b32_e32 v189, 0
	v_mov_b32_e32 v190, 0
	v_mov_b32_e32 v191, 0
	v_mov_b32_e32 v192, 0
	v_mov_b32_e32 v193, 0
	s_and_saveexec_b64 s[100:101], s[4:5]
	s_cbranch_execz .Lspp_4
	s_mov_b64 s[98:99], 0x2c00
	v_lshl_add_u64 v[194:195], v[172:173], 0, s[98:99]
	global_load_dwordx4 v[178:181], v[194:195], off
	s_mov_b64 s[98:99], 0x18c00
	v_lshl_add_u64 v[194:195], v[172:173], 0, s[98:99]
	global_load_dwordx4 v[182:185], v[194:195], off
	s_mov_b64 s[98:99], 0x2ec00
	v_lshl_add_u64 v[194:195], v[172:173], 0, s[98:99]
	global_load_dwordx4 v[186:189], v[194:195], off
	s_mov_b64 s[98:99], 0x44c00
	v_lshl_add_u64 v[194:195], v[172:173], 0, s[98:99]
	global_load_dwordx4 v[190:193], v[194:195], off
.Lspp_4:
	s_or_b64 exec, exec, s[100:101]
	s_nop 4
	v_mov_b32_dpp v164, v204 row_shl:1 row_mask:0xf bank_mask:0xf
	v_cndmask_b32_e64 v164, v18, v164, s[6:7]
	v_cndmask_b32_e64 v72, v165, v204, s[4:5]
	s_nop 0
	s_nop 0
	v_mov_b32_dpp v18, v133 row_shr:1 row_mask:0xf bank_mask:0xf bound_ctrl:1
	v_mov_b32_dpp v166, v133 row_shr:2 row_mask:0xf bank_mask:0xf bound_ctrl:1
	v_mov_b32_dpp v165, v205 row_shl:1 row_mask:0xf bank_mask:0xf bound_ctrl:1
	v_cndmask_b32_e64 v165, v18, v165, s[6:7]
	v_cndmask_b32_e64 v73, v166, v205, s[4:5]
	v_mov_b32_dpp v18, v134 row_shr:1 row_mask:0xf bank_mask:0xf bound_ctrl:1
	v_mov_b32_dpp v167, v134 row_shr:2 row_mask:0xf bank_mask:0xf bound_ctrl:1
	v_mov_b32_dpp v166, v206 row_shl:1 row_mask:0xf bank_mask:0xf bound_ctrl:1
	v_cndmask_b32_e64 v166, v18, v166, s[6:7]
	v_cndmask_b32_e64 v74, v167, v206, s[4:5]
	v_pk_fma_f32 v[132:133], v[132:133], v[144:145], v[148:149]
	v_mov_b32_dpp v18, v135 row_shr:1 row_mask:0xf bank_mask:0xf bound_ctrl:1
	v_mov_b32_dpp v167, v207 row_shl:1 row_mask:0xf bank_mask:0xf bound_ctrl:1
	v_pk_fma_f32 v[132:133], v[140:141], v[164:165], v[132:133]
	v_mov_b32_dpp v168, v135 row_shr:2 row_mask:0xf bank_mask:0xf bound_ctrl:1
	v_cndmask_b32_e64 v167, v18, v167, s[6:7]
	v_pk_fma_f32 v[134:135], v[134:135], v[146:147], v[150:151]
	v_pk_fma_f32 v[72:73], v[136:137], v[72:73], v[132:133]
	v_cndmask_b32_e64 v75, v168, v207, s[4:5]
	v_pk_fma_f32 v[134:135], v[142:143], v[166:167], v[134:135]
	v_mov_b32_dpp v18, v76 row_shr:1 row_mask:0xf bank_mask:0xf bound_ctrl:1
	v_mov_b32_dpp v133, v76 row_shr:2 row_mask:0xf bank_mask:0xf bound_ctrl:1
	v_mov_b32_dpp v132, v208 row_shl:1 row_mask:0xf bank_mask:0xf bound_ctrl:1
	v_pk_fma_f32 v[74:75], v[138:139], v[74:75], v[134:135]
	v_cndmask_b32_e64 v132, v18, v132, s[6:7]
	v_cndmask_b32_e64 v134, v133, v208, s[4:5]
	v_mov_b32_dpp v18, v77 row_shr:1 row_mask:0xf bank_mask:0xf bound_ctrl:1
	v_mov_b32_dpp v135, v77 row_shr:2 row_mask:0xf bank_mask:0xf bound_ctrl:1
	v_mov_b32_dpp v133, v209 row_shl:1 row_mask:0xf bank_mask:0xf bound_ctrl:1
	v_cndmask_b32_e64 v133, v18, v133, s[6:7]
	v_cndmask_b32_e64 v135, v135, v209, s[4:5]
	v_mov_b32_dpp v18, v78 row_shr:1 row_mask:0xf bank_mask:0xf bound_ctrl:1
	v_mov_b32_dpp v157, v78 row_shr:2 row_mask:0xf bank_mask:0xf bound_ctrl:1
	v_mov_b32_dpp v156, v210 row_shl:1 row_mask:0xf bank_mask:0xf bound_ctrl:1
	v_cndmask_b32_e64 v156, v18, v156, s[6:7]
	v_cndmask_b32_e64 v158, v157, v210, s[4:5]
	v_pk_fma_f32 v[76:77], v[76:77], v[144:145], v[148:149]
	v_mov_b32_dpp v18, v79 row_shr:1 row_mask:0xf bank_mask:0xf bound_ctrl:1
	v_mov_b32_dpp v157, v211 row_shl:1 row_mask:0xf bank_mask:0xf bound_ctrl:1
	v_cndmask_b32_e64 v157, v18, v157, s[6:7]
	v_pk_fma_f32 v[76:77], v[140:141], v[132:133], v[76:77]
	v_mov_b32_dpp v18, v80 row_shr:1 row_mask:0xf bank_mask:0xf bound_ctrl:1
	v_mov_b32_dpp v133, v80 row_shr:2 row_mask:0xf bank_mask:0xf bound_ctrl:1
	v_mov_b32_dpp v132, v212 row_shl:1 row_mask:0xf bank_mask:0xf bound_ctrl:1
	v_pk_fma_f32 v[76:77], v[136:137], v[134:135], v[76:77]
	v_cndmask_b32_e64 v132, v18, v132, s[6:7]
	v_cndmask_b32_e64 v134, v133, v212, s[4:5]
	v_mov_b32_dpp v164, v79 row_shr:2 row_mask:0xf bank_mask:0xf bound_ctrl:1
	v_pk_fma_f32 v[78:79], v[78:79], v[146:147], v[150:151]
	v_mov_b32_dpp v18, v81 row_shr:1 row_mask:0xf bank_mask:0xf bound_ctrl:1
	v_mov_b32_dpp v133, v213 row_shl:1 row_mask:0xf bank_mask:0xf bound_ctrl:1
	v_pk_fma_f32 v[78:79], v[142:143], v[156:157], v[78:79]
	v_cndmask_b32_e64 v133, v18, v133, s[6:7]
	v_cndmask_b32_e64 v159, v164, v211, s[4:5]
	v_mov_b32_dpp v18, v82 row_shr:1 row_mask:0xf bank_mask:0xf bound_ctrl:1
	v_mov_b32_dpp v157, v82 row_shr:2 row_mask:0xf bank_mask:0xf bound_ctrl:1
	v_mov_b32_dpp v156, v214 row_shl:1 row_mask:0xf bank_mask:0xf bound_ctrl:1
	v_pk_fma_f32 v[78:79], v[138:139], v[158:159], v[78:79]
	v_cndmask_b32_e64 v156, v18, v156, s[6:7]
	v_cndmask_b32_e64 v158, v157, v214, s[4:5]
	v_mov_b32_dpp v135, v81 row_shr:2 row_mask:0xf bank_mask:0xf bound_ctrl:1
	v_mov_b32_dpp v18, v83 row_shr:1 row_mask:0xf bank_mask:0xf bound_ctrl:1
	v_mov_b32_dpp v157, v215 row_shl:1 row_mask:0xf bank_mask:0xf bound_ctrl:1
	v_pk_fma_f32 v[80:81], v[80:81], v[144:145], v[148:149]
	v_cndmask_b32_e64 v157, v18, v157, s[6:7]
	v_pk_fma_f32 v[80:81], v[140:141], v[132:133], v[80:81]
	v_cndmask_b32_e64 v135, v135, v213, s[4:5]
	v_mov_b32_dpp v18, v96 row_shr:1 row_mask:0xf bank_mask:0xf bound_ctrl:1
	v_mov_b32_dpp v133, v96 row_shr:2 row_mask:0xf bank_mask:0xf bound_ctrl:1
	v_mov_b32_dpp v132, v216 row_shl:1 row_mask:0xf bank_mask:0xf bound_ctrl:1
	v_pk_fma_f32 v[80:81], v[136:137], v[134:135], v[80:81]
	v_cndmask_b32_e64 v132, v18, v132, s[6:7]
;     __device__ __forceinline__ f32x4 conv4s(const f32x4 c4, const f32x4 pv, int t, const f32x4 w0, const f32x4 w1, const f32x4 w2, const f32x4 bsv) const {
;         f32x4 p1, p2;
; #pragma unroll
;         for (int e = 0; e < 4; ++e) { p1[e] = dpp_f<0x111>(0.f, c4[e]); p2[e] = dpp_f<0x112>(0.f, c4[e]); const float q1 = dpp_f<0x101>(0.f, pv[e]);
;             p1[e] = t == 0 ? q1 : p1[e]; p2[e] = t < 2 ? pv[e] : p2[e]; }
;         f32x4 uu = bsv + w2 * c4 + w1 * p1 + w0 * p2;
;         asm volatile("" : "+v"(uu));
;         return uu;
;     __device__ __forceinline__ void sample(f32x4 (&acc)[2][2][4][2], const Unit& u, int row0t, int wr, int wc, int fr, int fq) const {
;     ...
;         for (int step = 0; step < 4; ++step) {
;             const int n = (step == 1 || step == 2) ? 1 : 0, ai = step >> 1;
;             f32x4 w0, w1, w2, bsv;
;             if (step != 2) { const unsigned cso = (unsigned)((DFF + ca + 4 * n) * 4);
;                 w0 = *(const f32x4*)((const char*)cw + cso); w1 = *(const f32x4*)((const char*)(cw + DFF2) + cso); w2 = *(const f32x4*)((const char*)(cw + 2 * DFF2) + cso); bsv = *(const f32x4*)((const char*)cb + cso);
;                 wk[0] = w0; wk[1] = w1; wk[2] = w2; wk[3] = bsv; }
;             else { w0 = wk[0]; w1 = wk[1]; w2 = wk[2]; bsv = wk[3]; }
; #pragma unroll
;             for (int mp = 0; mp < 4; mp += 4) {
;             f32x4 pv[4];
; #pragma unroll
;             for (int k = 0; k < 4; ++k) { pv[k] = (f32x4){0.f, 0.f, 0.f, 0.f}; if (t < 2) pv[k] = *(const f32x4*)((const char*)st + stoff + (unsigned)(((16 * ai + 2 * (mp + k)) * 2 * DFF2 + DFF + 4 * n) * 4)); }
	v_cndmask_b32_e64 v134, v133, v216, s[4:5]
	v_mov_b32_dpp v18, v97 row_shr:1 row_mask:0xf bank_mask:0xf bound_ctrl:1
	v_mov_b32_dpp v135, v97 row_shr:2 row_mask:0xf bank_mask:0xf bound_ctrl:1
	v_mov_b32_dpp v133, v217 row_shl:1 row_mask:0xf bank_mask:0xf bound_ctrl:1
	v_cndmask_b32_e64 v133, v18, v133, s[6:7]
	v_cndmask_b32_e64 v135, v135, v217, s[4:5]
	v_mov_b32_dpp v18, v98 row_shr:1 row_mask:0xf bank_mask:0xf bound_ctrl:1
	v_mov_b32_dpp v153, v98 row_shr:2 row_mask:0xf bank_mask:0xf bound_ctrl:1
	v_mov_b32_dpp v152, v218 row_shl:1 row_mask:0xf bank_mask:0xf bound_ctrl:1
	v_mov_b32_dpp v159, v83 row_shr:2 row_mask:0xf bank_mask:0xf bound_ctrl:1
	v_pk_fma_f32 v[82:83], v[82:83], v[146:147], v[150:151]
	v_cndmask_b32_e64 v152, v18, v152, s[6:7]
	v_cndmask_b32_e64 v154, v153, v218, s[4:5]
	v_pk_fma_f32 v[82:83], v[142:143], v[156:157], v[82:83]
	v_mov_b32_dpp v18, v99 row_shr:1 row_mask:0xf bank_mask:0xf bound_ctrl:1
	v_mov_b32_dpp v153, v219 row_shl:1 row_mask:0xf bank_mask:0xf bound_ctrl:1
	v_cndmask_b32_e64 v153, v18, v153, s[6:7]
	v_mov_b32_dpp v156, v99 row_shr:2 row_mask:0xf bank_mask:0xf bound_ctrl:1
	v_pk_fma_f32 v[98:99], v[98:99], v[146:147], v[150:151]
	v_pk_fma_f32 v[96:97], v[96:97], v[144:145], v[148:149]
	v_cndmask_b32_e64 v159, v159, v215, s[4:5]
	v_cndmask_b32_e64 v155, v156, v219, s[4:5]
	v_pk_fma_f32 v[98:99], v[142:143], v[152:153], v[98:99]
	v_pk_fma_f32 v[96:97], v[140:141], v[132:133], v[96:97]
	v_pk_fma_f32 v[82:83], v[138:139], v[158:159], v[82:83]
	v_pk_fma_f32 v[98:99], v[138:139], v[154:155], v[98:99]
	v_pk_fma_f32 v[96:97], v[136:137], v[134:135], v[96:97]
	s_nop 0
	v_add_u32_e32 v170, 0x2c00, v176
	global_load_dwordx4 v[136:139], v170, s[0:1]
	global_load_dwordx4 v[140:143], v170, s[8:9]
	global_load_dwordx4 v[132:135], v170, s[96:97]
	global_load_dwordx4 v[144:147], v170, s[66:67]
	v_mov_b32_e32 v152, 0
	v_mov_b32_e32 v156, 0
	v_mov_b32_e32 v157, 0
	v_mov_b32_e32 v158, 0
	v_mov_b32_e32 v159, 0
	v_mov_b32_e32 v153, 0
	v_mov_b32_e32 v154, 0
	v_mov_b32_e32 v155, 0
	v_mov_b32_e32 v148, 0
	v_mov_b32_e32 v166, 0
	v_mov_b32_e32 v167, 0
	v_mov_b32_e32 v168, 0
	v_mov_b32_e32 v169, 0
	v_mov_b32_e32 v149, 0
	v_mov_b32_e32 v150, 0
	v_mov_b32_e32 v151, 0
	s_nop 0
	s_nop 0
	v_mov_b32_e32 v160, v19
	v_mov_b32_dpp v18, v92 row_shr:1 row_mask:0xf bank_mask:0xf bound_ctrl:1
	v_mov_b32_dpp v161, v92 row_shr:2 row_mask:0xf bank_mask:0xf bound_ctrl:1
	s_waitcnt vmcnt(0)
	v_mov_b32_e32 v204, 0
	v_mov_b32_e32 v205, 0
	v_mov_b32_e32 v206, 0
	v_mov_b32_e32 v207, 0
	v_mov_b32_e32 v208, 0
	v_mov_b32_e32 v209, 0
	v_mov_b32_e32 v210, 0
	v_mov_b32_e32 v211, 0
	v_mov_b32_e32 v212, 0
	v_mov_b32_e32 v213, 0
	v_mov_b32_e32 v214, 0
	v_mov_b32_e32 v215, 0
	v_mov_b32_e32 v216, 0
	v_mov_b32_e32 v217, 0
	v_mov_b32_e32 v218, 0
	v_mov_b32_e32 v219, 0
	s_and_saveexec_b64 s[100:101], s[4:5]
	s_cbranch_execz .Lspp_5
	s_mov_b64 s[98:99], 0x2c10
	v_lshl_add_u64 v[194:195], v[172:173], 0, s[98:99]
	global_load_dwordx4 v[204:207], v[194:195], off
	s_mov_b64 s[98:99], 0x18c10
	v_lshl_add_u64 v[194:195], v[172:173], 0, s[98:99]
	global_load_dwordx4 v[208:211], v[194:195], off
	s_mov_b64 s[98:99], 0x2ec10
	v_lshl_add_u64 v[194:195], v[172:173], 0, s[98:99]
	global_load_dwordx4 v[212:215], v[194:195], off
	s_mov_b64 s[98:99], 0x44c10
	v_lshl_add_u64 v[194:195], v[172:173], 0, s[98:99]
	global_load_dwordx4 v[216:219], v[194:195], off
.Lspp_5:
	s_or_b64 exec, exec, s[100:101]
	s_nop 4
	v_mov_b32_dpp v160, v178 row_shl:1 row_mask:0xf bank_mask:0xf
	v_cndmask_b32_e64 v160, v18, v160, s[6:7]
	v_cndmask_b32_e64 v156, v161, v178, s[4:5]
	s_nop 0
	s_nop 0
	v_mov_b32_dpp v18, v93 row_shr:1 row_mask:0xf bank_mask:0xf bound_ctrl:1
	v_mov_b32_dpp v162, v93 row_shr:2 row_mask:0xf bank_mask:0xf bound_ctrl:1
	v_mov_b32_dpp v161, v179 row_shl:1 row_mask:0xf bank_mask:0xf bound_ctrl:1
	v_cndmask_b32_e64 v161, v18, v161, s[6:7]
	v_cndmask_b32_e64 v157, v162, v179, s[4:5]
	v_mov_b32_dpp v18, v94 row_shr:1 row_mask:0xf bank_mask:0xf bound_ctrl:1
	v_mov_b32_dpp v163, v94 row_shr:2 row_mask:0xf bank_mask:0xf bound_ctrl:1
	v_mov_b32_dpp v162, v180 row_shl:1 row_mask:0xf bank_mask:0xf bound_ctrl:1
	v_cndmask_b32_e64 v162, v18, v162, s[6:7]
	v_cndmask_b32_e64 v158, v163, v180, s[4:5]
	v_mov_b32_dpp v18, v95 row_shr:1 row_mask:0xf bank_mask:0xf bound_ctrl:1
	v_mov_b32_dpp v163, v181 row_shl:1 row_mask:0xf bank_mask:0xf bound_ctrl:1
	v_mov_b32_dpp v164, v95 row_shr:2 row_mask:0xf bank_mask:0xf bound_ctrl:1
	v_cndmask_b32_e64 v163, v18, v163, s[6:7]
	v_pk_fma_f32 v[94:95], v[94:95], v[142:143], v[146:147]
	v_pk_fma_f32 v[92:93], v[92:93], v[140:141], v[144:145]
	v_cndmask_b32_e64 v159, v164, v181, s[4:5]
	v_pk_fma_f32 v[94:95], v[138:139], v[162:163], v[94:95]
	v_pk_fma_f32 v[92:93], v[136:137], v[160:161], v[92:93]
	v_pk_fma_f32 v[164:165], v[134:135], v[158:159], v[94:95]
	v_pk_fma_f32 v[162:163], v[132:133], v[156:157], v[92:93]
	s_nop 0
	v_mov_b32_dpp v18, v88 row_shr:1 row_mask:0xf bank_mask:0xf bound_ctrl:1
	v_mov_b32_dpp v93, v88 row_shr:2 row_mask:0xf bank_mask:0xf bound_ctrl:1
	v_mov_b32_dpp v92, v182 row_shl:1 row_mask:0xf bank_mask:0xf bound_ctrl:1
	v_cndmask_b32_e64 v92, v18, v92, s[6:7]
	v_cndmask_b32_e64 v94, v93, v182, s[4:5]
	v_mov_b32_dpp v18, v89 row_shr:1 row_mask:0xf bank_mask:0xf bound_ctrl:1
	v_mov_b32_dpp v95, v89 row_shr:2 row_mask:0xf bank_mask:0xf bound_ctrl:1
	v_mov_b32_dpp v93, v183 row_shl:1 row_mask:0xf bank_mask:0xf bound_ctrl:1
	v_cndmask_b32_e64 v93, v18, v93, s[6:7]
	v_cndmask_b32_e64 v95, v95, v183, s[4:5]
	v_mov_b32_dpp v18, v90 row_shr:1 row_mask:0xf bank_mask:0xf bound_ctrl:1
	v_mov_b32_dpp v153, v90 row_shr:2 row_mask:0xf bank_mask:0xf bound_ctrl:1
; __device__ __forceinline__ unsigned cvt_pk_bf16(float lo, float hi) { const bf16x2_t r = __builtin_convertvector((f32x2){lo, hi}, bf16x2_t); return __builtin_bit_cast(unsigned, r); }
;     __device__ __forceinline__ f32x4 conv4s(const f32x4 c4, const f32x4 pv, int t, const f32x4 w0, const f32x4 w1, const f32x4 w2, const f32x4 bsv) const {
;         f32x4 p1, p2;
; #pragma unroll
;         for (int e = 0; e < 4; ++e) { p1[e] = dpp_f<0x111>(0.f, c4[e]); p2[e] = dpp_f<0x112>(0.f, c4[e]); const float q1 = dpp_f<0x101>(0.f, pv[e]);
;             p1[e] = t == 0 ? q1 : p1[e]; p2[e] = t < 2 ? pv[e] : p2[e]; }
;         f32x4 uu = bsv + w2 * c4 + w1 * p1 + w0 * p2;
;         asm volatile("" : "+v"(uu));
;         return uu;
;     __device__ __forceinline__ void sample(f32x4 (&acc)[2][2][4][2], const Unit& u, int row0t, int wr, int wc, int fr, int fq) const {
;     ...
;             if (step != 2) { const unsigned cso = (unsigned)((DFF + ca + 4 * n) * 4);
;                 w0 = *(const f32x4*)((const char*)cw + cso); w1 = *(const f32x4*)((const char*)(cw + DFF2) + cso); w2 = *(const f32x4*)((const char*)(cw + 2 * DFF2) + cso); bsv = *(const f32x4*)((const char*)cb + cso);
;                 wk[0] = w0; wk[1] = w1; wk[2] = w2; wk[3] = bsv; }
;             else { w0 = wk[0]; w1 = wk[1]; w2 = wk[2]; bsv = wk[3]; }
; #pragma unroll
;             for (int mp = 0; mp < 4; mp += 4) {
;             f32x4 pv[4];
; #pragma unroll
;             for (int k = 0; k < 4; ++k) { pv[k] = (f32x4){0.f, 0.f, 0.f, 0.f}; if (t < 2) pv[k] = *(const f32x4*)((const char*)st + stoff + (unsigned)(((16 * ai + 2 * (mp + k)) * 2 * DFF2 + DFF + 4 * n) * 4)); }
; #pragma unroll
;             for (int k = 0; k < 4; ++k) { const int m = mp + k;
;                 const f32x4 uu = conv4s(acc[ai][1][m][n], pv[k], t, w0, w1, w2, bsv);
;                 const f32x4 ua = acc[ai][0][m][n];
;                 u32x2 w; w.x = cvt_pk_bf16(silu_f(ua[0]) * uu[0], silu_f(ua[1]) * uu[1]); w.y = cvt_pk_bf16(silu_f(ua[2]) * uu[2], silu_f(ua[3]) * uu[3]);
;                 if ((step & 1) == 0) pend[m] = w;
;                 else { u32x4 o; if (n == 1) { o.x = pend[m].x; o.y = pend[m].y; o.z = w.x; o.w = w.y; } else { o.x = w.x; o.y = w.y; o.z = pend[m].x; o.w = pend[m].y; }
;                     *(u32x4*)((char*)act + rowoff0 + (unsigned)((ai * HALF + m * 16) * DFF * 2) + (unsigned)(ca * 2)) = o; }
	v_mov_b32_dpp v152, v184 row_shl:1 row_mask:0xf bank_mask:0xf bound_ctrl:1
	v_cndmask_b32_e64 v152, v18, v152, s[6:7]
	v_cndmask_b32_e64 v154, v153, v184, s[4:5]
	v_mov_b32_dpp v18, v91 row_shr:1 row_mask:0xf bank_mask:0xf bound_ctrl:1
	v_mov_b32_dpp v153, v185 row_shl:1 row_mask:0xf bank_mask:0xf bound_ctrl:1
	v_mov_b32_dpp v156, v91 row_shr:2 row_mask:0xf bank_mask:0xf bound_ctrl:1
	v_cndmask_b32_e64 v153, v18, v153, s[6:7]
	v_pk_fma_f32 v[90:91], v[90:91], v[142:143], v[146:147]
	v_pk_fma_f32 v[88:89], v[88:89], v[140:141], v[144:145]
	v_cndmask_b32_e64 v155, v156, v185, s[4:5]
	v_pk_fma_f32 v[90:91], v[138:139], v[152:153], v[90:91]
	v_pk_fma_f32 v[88:89], v[136:137], v[92:93], v[88:89]
	v_pk_fma_f32 v[160:161], v[134:135], v[154:155], v[90:91]
	v_pk_fma_f32 v[158:159], v[132:133], v[94:95], v[88:89]
	s_nop 0
	v_mov_b32_dpp v18, v84 row_shr:1 row_mask:0xf bank_mask:0xf bound_ctrl:1
	v_mov_b32_dpp v89, v84 row_shr:2 row_mask:0xf bank_mask:0xf bound_ctrl:1
	v_mov_b32_dpp v88, v186 row_shl:1 row_mask:0xf bank_mask:0xf bound_ctrl:1
	v_cndmask_b32_e64 v88, v18, v88, s[6:7]
	v_cndmask_b32_e64 v90, v89, v186, s[4:5]
	v_mov_b32_dpp v18, v85 row_shr:1 row_mask:0xf bank_mask:0xf bound_ctrl:1
	v_mov_b32_dpp v89, v187 row_shl:1 row_mask:0xf bank_mask:0xf bound_ctrl:1
	v_cndmask_b32_e64 v89, v18, v89, s[6:7]
	v_mov_b32_dpp v93, v86 row_shr:2 row_mask:0xf bank_mask:0xf bound_ctrl:1
	v_mov_b32_dpp v18, v86 row_shr:1 row_mask:0xf bank_mask:0xf bound_ctrl:1
	v_mov_b32_dpp v92, v188 row_shl:1 row_mask:0xf bank_mask:0xf bound_ctrl:1
	v_cndmask_b32_e64 v92, v18, v92, s[6:7]
	v_cndmask_b32_e64 v94, v93, v188, s[4:5]
	v_mov_b32_dpp v18, v87 row_shr:1 row_mask:0xf bank_mask:0xf bound_ctrl:1
	v_mov_b32_dpp v93, v189 row_shl:1 row_mask:0xf bank_mask:0xf bound_ctrl:1
	v_mov_b32_dpp v91, v85 row_shr:2 row_mask:0xf bank_mask:0xf bound_ctrl:1
	v_mov_b32_dpp v95, v87 row_shr:2 row_mask:0xf bank_mask:0xf bound_ctrl:1
	v_cndmask_b32_e64 v93, v18, v93, s[6:7]
	v_pk_fma_f32 v[86:87], v[86:87], v[142:143], v[146:147]
	v_pk_fma_f32 v[84:85], v[84:85], v[140:141], v[144:145]
	v_cndmask_b32_e64 v91, v91, v187, s[4:5]
	v_cndmask_b32_e64 v95, v95, v189, s[4:5]
	v_pk_fma_f32 v[86:87], v[138:139], v[92:93], v[86:87]
	v_pk_fma_f32 v[84:85], v[136:137], v[88:89], v[84:85]
	v_pk_fma_f32 v[156:157], v[134:135], v[94:95], v[86:87]
	v_pk_fma_f32 v[154:155], v[132:133], v[90:91], v[84:85]
	s_nop 0
	v_mov_b32_dpp v18, v68 row_shr:1 row_mask:0xf bank_mask:0xf bound_ctrl:1
	v_mov_b32_dpp v85, v68 row_shr:2 row_mask:0xf bank_mask:0xf bound_ctrl:1
	v_mov_b32_dpp v84, v190 row_shl:1 row_mask:0xf bank_mask:0xf bound_ctrl:1
	v_cndmask_b32_e64 v84, v18, v84, s[6:7]
	v_cndmask_b32_e64 v86, v85, v190, s[4:5]
	v_mov_b32_dpp v18, v69 row_shr:1 row_mask:0xf bank_mask:0xf bound_ctrl:1
	v_mov_b32_dpp v85, v191 row_shl:1 row_mask:0xf bank_mask:0xf bound_ctrl:1
	v_cndmask_b32_e64 v85, v18, v85, s[6:7]
	v_mov_b32_dpp v89, v70 row_shr:2 row_mask:0xf bank_mask:0xf bound_ctrl:1
	v_mov_b32_dpp v18, v70 row_shr:1 row_mask:0xf bank_mask:0xf bound_ctrl:1
	v_mov_b32_dpp v88, v192 row_shl:1 row_mask:0xf bank_mask:0xf bound_ctrl:1
	v_cndmask_b32_e64 v88, v18, v88, s[6:7]
	v_cndmask_b32_e64 v90, v89, v192, s[4:5]
	v_mov_b32_dpp v18, v71 row_shr:1 row_mask:0xf bank_mask:0xf bound_ctrl:1
	v_mov_b32_dpp v89, v193 row_shl:1 row_mask:0xf bank_mask:0xf bound_ctrl:1
	v_mov_b32_dpp v87, v69 row_shr:2 row_mask:0xf bank_mask:0xf bound_ctrl:1
	v_mov_b32_dpp v91, v71 row_shr:2 row_mask:0xf bank_mask:0xf bound_ctrl:1
	v_cndmask_b32_e64 v89, v18, v89, s[6:7]
	v_pk_fma_f32 v[70:71], v[70:71], v[142:143], v[146:147]
	v_pk_fma_f32 v[68:69], v[68:69], v[140:141], v[144:145]
	v_cndmask_b32_e64 v87, v87, v191, s[4:5]
	v_cndmask_b32_e64 v91, v91, v193, s[4:5]
	v_pk_fma_f32 v[70:71], v[138:139], v[88:89], v[70:71]
	v_pk_fma_f32 v[68:69], v[136:137], v[84:85], v[68:69]
	v_pk_fma_f32 v[152:153], v[134:135], v[90:91], v[70:71]
	v_pk_fma_f32 v[150:151], v[132:133], v[86:87], v[68:69]
	s_nop 0
	v_add_u32_e32 v18, 0x2c10, v176
	global_load_dwordx4 v[84:87], v18, s[0:1]
	global_load_dwordx4 v[88:91], v18, s[8:9]
	global_load_dwordx4 v[68:71], v18, s[96:97]
	global_load_dwordx4 v[92:95], v18, s[66:67]
	v_mov_b32_e32 v140, 0
	v_mov_b32_e32 v144, 0
	v_mov_b32_e32 v145, 0
	v_mov_b32_e32 v146, 0
	v_mov_b32_e32 v147, 0
	v_mov_b32_e32 v141, 0
	v_mov_b32_e32 v142, 0
	v_mov_b32_e32 v143, 0
	v_mov_b32_e32 v132, 0
	v_mov_b32_e32 v136, 0
	v_mov_b32_e32 v137, 0
	v_mov_b32_e32 v138, 0
	v_mov_b32_e32 v139, 0
	v_mov_b32_e32 v133, 0
	v_mov_b32_e32 v134, 0
	v_mov_b32_e32 v135, 0
	v_mul_f32_e32 v18, 0xbfb8aa3b, v114
	v_exp_f32_e32 v18, v18
	s_movk_i32 s2, 0x1600
	v_add_f32_e32 v18, 1.0, v18
	v_rcp_f32_e32 v148, v18
	v_mul_f32_e32 v18, 0xbfb8aa3b, v115
	v_exp_f32_e32 v18, v18
	s_nop 0
	v_add_f32_e32 v18, 1.0, v18
	v_rcp_f32_e32 v149, v18
	v_mul_f32_e32 v18, 0xbfb8aa3b, v112
	v_exp_f32_e32 v18, v18
	v_pk_mul_f32 v[114:115], v[114:115], v[148:149]
	s_nop 0
	v_pk_mul_f32 v[114:115], v[114:115], v[164:165]
	v_add_f32_e32 v18, 1.0, v18
	v_cvt_pk_bf16_f32 v149, v114, v115
	v_rcp_f32_e32 v114, v18
	v_mul_f32_e32 v18, 0xbfb8aa3b, v113
	v_exp_f32_e32 v18, v18
	s_nop 0
	v_add_f32_e32 v18, 1.0, v18
	v_rcp_f32_e32 v115, v18
	v_mul_f32_e32 v18, 0xbfb8aa3b, v110
	v_exp_f32_e32 v18, v18
	v_pk_mul_f32 v[112:113], v[112:113], v[114:115]
	s_nop 0
	v_pk_mul_f32 v[112:113], v[112:113], v[162:163]
	v_add_f32_e32 v18, 1.0, v18
	v_cvt_pk_bf16_f32 v148, v112, v113
	v_rcp_f32_e32 v112, v18
	v_mul_f32_e32 v18, 0xbfb8aa3b, v111
	v_exp_f32_e32 v18, v18
	v_mov_b32_e32 v114, v19
	v_mov_b32_e32 v115, v19
	v_add_f32_e32 v18, 1.0, v18
	v_rcp_f32_e32 v113, v18
	v_mul_f32_e32 v18, 0xbfb8aa3b, v108
	v_exp_f32_e32 v18, v18
	s_waitcnt vmcnt(0)
	v_mov_b32_e32 v178, 0
	v_mov_b32_e32 v179, 0
	v_mov_b32_e32 v180, 0
	v_mov_b32_e32 v181, 0
	v_mov_b32_e32 v182, 0
	v_mov_b32_e32 v183, 0
	v_mov_b32_e32 v184, 0
	v_mov_b32_e32 v185, 0
	v_mov_b32_e32 v186, 0
	v_mov_b32_e32 v187, 0
	v_mov_b32_e32 v188, 0
	v_mov_b32_e32 v189, 0
	v_mov_b32_e32 v190, 0
	v_mov_b32_e32 v191, 0
	v_mov_b32_e32 v192, 0
	v_mov_b32_e32 v193, 0
	s_and_saveexec_b64 s[100:101], s[4:5]
	s_cbranch_execz .Lspp_6
	s_mov_b64 s[98:99], 0xb2c10
	v_lshl_add_u64 v[194:195], v[172:173], 0, s[98:99]
	global_load_dwordx4 v[178:181], v[194:195], off
	s_mov_b64 s[98:99], 0xc8c10
	v_lshl_add_u64 v[194:195], v[172:173], 0, s[98:99]
	global_load_dwordx4 v[182:185], v[194:195], off
	s_mov_b64 s[98:99], 0xdec10
	v_lshl_add_u64 v[194:195], v[172:173], 0, s[98:99]
	global_load_dwordx4 v[186:189], v[194:195], off
	s_mov_b64 s[98:99], 0xf4c10
	v_lshl_add_u64 v[194:195], v[172:173], 0, s[98:99]
	global_load_dwordx4 v[190:193], v[194:195], off
; __device__ __forceinline__ unsigned cvt_pk_bf16(float lo, float hi) { const bf16x2_t r = __builtin_convertvector((f32x2){lo, hi}, bf16x2_t); return __builtin_bit_cast(unsigned, r); }
; __device__ __forceinline__ float silu_f(float x) { return x * __builtin_amdgcn_rcpf(1.0f + __expf(-x)); }
;     __device__ __forceinline__ f32x4 conv4s(const f32x4 c4, const f32x4 pv, int t, const f32x4 w0, const f32x4 w1, const f32x4 w2, const f32x4 bsv) const {
;         f32x4 p1, p2;
; #pragma unroll
;         for (int e = 0; e < 4; ++e) { p1[e] = dpp_f<0x111>(0.f, c4[e]); p2[e] = dpp_f<0x112>(0.f, c4[e]); const float q1 = dpp_f<0x101>(0.f, pv[e]);
;             p1[e] = t == 0 ? q1 : p1[e]; p2[e] = t < 2 ? pv[e] : p2[e]; }
;         f32x4 uu = bsv + w2 * c4 + w1 * p1 + w0 * p2;
;         asm volatile("" : "+v"(uu));
;         return uu;
;     __device__ __forceinline__ void sample(f32x4 (&acc)[2][2][4][2], const Unit& u, int row0t, int wr, int wc, int fr, int fq) const {
;     ...
;             for (int k = 0; k < 4; ++k) { pv[k] = (f32x4){0.f, 0.f, 0.f, 0.f}; if (t < 2) pv[k] = *(const f32x4*)((const char*)st + stoff + (unsigned)(((16 * ai + 2 * (mp + k)) * 2 * DFF2 + DFF + 4 * n) * 4)); }
; #pragma unroll
;             for (int k = 0; k < 4; ++k) { const int m = mp + k;
;                 const f32x4 uu = conv4s(acc[ai][1][m][n], pv[k], t, w0, w1, w2, bsv);
;                 const f32x4 ua = acc[ai][0][m][n];
;                 u32x2 w; w.x = cvt_pk_bf16(silu_f(ua[0]) * uu[0], silu_f(ua[1]) * uu[1]); w.y = cvt_pk_bf16(silu_f(ua[2]) * uu[2], silu_f(ua[3]) * uu[3]);
;                 if ((step & 1) == 0) pend[m] = w;
;                 else { u32x4 o; if (n == 1) { o.x = pend[m].x; o.y = pend[m].y; o.z = w.x; o.w = w.y; } else { o.x = w.x; o.y = w.y; o.z = pend[m].x; o.w = pend[m].y; }
;                     *(u32x4*)((char*)act + rowoff0 + (unsigned)((ai * HALF + m * 16) * DFF * 2) + (unsigned)(ca * 2)) = o; }
.Lspp_6:
	s_or_b64 exec, exec, s[100:101]
	s_nop 4
	v_mov_b32_dpp v114, v206 row_shl:1 row_mask:0xf bank_mask:0xf
	v_pk_mul_f32 v[110:111], v[110:111], v[112:113]
	v_mov_b32_dpp v115, v67 row_shr:2 row_mask:0xf bank_mask:0xf
	v_add_f32_e32 v18, 1.0, v18
	v_rcp_f32_e32 v112, v18
	v_mul_f32_e32 v18, 0xbfb8aa3b, v109
	v_exp_f32_e32 v18, v18
	v_pk_mul_f32 v[110:111], v[110:111], v[160:161]
	v_cndmask_b32_e64 v115, v115, v207, s[4:5]
	v_cvt_pk_bf16_f32 v111, v110, v111
	v_add_f32_e32 v18, 1.0, v18
	v_rcp_f32_e32 v113, v18
	v_mul_f32_e32 v18, 0xbfb8aa3b, v106
	v_exp_f32_e32 v18, v18
	v_pk_mul_f32 v[108:109], v[108:109], v[112:113]
	s_nop 0
	v_pk_mul_f32 v[108:109], v[108:109], v[158:159]
	v_add_f32_e32 v18, 1.0, v18
	v_cvt_pk_bf16_f32 v110, v108, v109
	v_rcp_f32_e32 v108, v18
	v_mul_f32_e32 v18, 0xbfb8aa3b, v107
	v_exp_f32_e32 v18, v18
	s_nop 0
	s_nop 0
	v_add_f32_e32 v18, 1.0, v18
	v_rcp_f32_e32 v109, v18
	v_mul_f32_e32 v18, 0xbfb8aa3b, v104
	v_exp_f32_e32 v18, v18
	v_mov_b32_dpp v112, v205 row_shl:1 row_mask:0xf bank_mask:0xf bound_ctrl:1
	v_pk_mul_f32 v[106:107], v[106:107], v[108:109]
	v_mov_b32_dpp v113, v66 row_shr:2 row_mask:0xf bank_mask:0xf bound_ctrl:1
	v_add_f32_e32 v18, 1.0, v18
	v_rcp_f32_e32 v108, v18
	v_mul_f32_e32 v18, 0xbfb8aa3b, v105
	v_exp_f32_e32 v18, v18
	v_pk_mul_f32 v[106:107], v[106:107], v[156:157]
	v_add_f32_e32 v18, 1.0, v18
	v_rcp_f32_e32 v109, v18
	v_mul_f32_e32 v18, 0xbfb8aa3b, v102
	v_exp_f32_e32 v18, v18
	v_cvt_pk_bf16_f32 v107, v106, v107
	v_pk_mul_f32 v[104:105], v[104:105], v[108:109]
	s_nop 0
	v_pk_mul_f32 v[104:105], v[104:105], v[154:155]
	v_add_f32_e32 v18, 1.0, v18
	v_cvt_pk_bf16_f32 v106, v104, v105
	v_rcp_f32_e32 v104, v18
	v_mul_f32_e32 v18, 0xbfb8aa3b, v103
	v_exp_f32_e32 v18, v18
	v_mov_b32_dpp v108, v204 row_shl:1 row_mask:0xf bank_mask:0xf bound_ctrl:1
	s_nop 0
	v_add_f32_e32 v18, 1.0, v18
	v_rcp_f32_e32 v105, v18
	v_mul_f32_e32 v18, 0xbfb8aa3b, v100
	v_exp_f32_e32 v18, v18
	v_mov_b32_dpp v109, v65 row_shr:2 row_mask:0xf bank_mask:0xf bound_ctrl:1
	v_pk_mul_f32 v[102:103], v[102:103], v[104:105]
	v_cndmask_b32_e64 v109, v109, v205, s[4:5]
	v_add_f32_e32 v18, 1.0, v18
	v_rcp_f32_e32 v104, v18
	v_mul_f32_e32 v18, 0xbfb8aa3b, v101
	v_exp_f32_e32 v18, v18
	v_pk_mul_f32 v[102:103], v[102:103], v[152:153]
	v_add_f32_e32 v18, 1.0, v18
	v_rcp_f32_e32 v105, v18
	v_mul_lo_u32 v18, v174, s2
	v_cvt_pk_bf16_f32 v103, v102, v103
	v_pk_mul_f32 v[100:101], v[100:101], v[104:105]
	s_nop 0
	s_nop 0
	v_pk_mul_f32 v[100:101], v[100:101], v[150:151]
	v_mov_b32_dpp v104, v64 row_shr:1 row_mask:0xf bank_mask:0xf bound_ctrl:1
	v_mov_b32_dpp v105, v64 row_shr:2 row_mask:0xf bank_mask:0xf bound_ctrl:1
	v_cndmask_b32_e64 v104, v104, v108, s[6:7]
	v_cndmask_b32_e64 v108, v105, v204, s[4:5]
	v_cvt_pk_bf16_f32 v102, v100, v101
	v_mov_b32_dpp v105, v65 row_shr:1 row_mask:0xf bank_mask:0xf bound_ctrl:1
	v_cndmask_b32_e64 v105, v105, v112, s[6:7]
	v_pk_fma_f32 v[64:65], v[64:65], v[88:89], v[92:93]
	s_nop 0
	v_pk_fma_f32 v[64:65], v[84:85], v[104:105], v[64:65]
	v_mul_f32_e32 v104, 0xbfb8aa3b, v128
	v_mul_f32_e32 v105, 0xbfb8aa3b, v129
	v_exp_f32_e32 v104, v104
	v_exp_f32_e32 v105, v105
	v_mov_b32_dpp v112, v66 row_shr:1 row_mask:0xf bank_mask:0xf bound_ctrl:1
	v_cndmask_b32_e64 v112, v112, v114, s[6:7]
	v_cndmask_b32_e64 v114, v113, v206, s[4:5]
	s_nop 0
	v_add_f32_e32 v104, 1.0, v104
	v_add_f32_e32 v105, 1.0, v105
	v_mov_b32_dpp v113, v67 row_shr:1 row_mask:0xf bank_mask:0xf bound_ctrl:1
	v_mov_b32_dpp v144, v207 row_shl:1 row_mask:0xf bank_mask:0xf bound_ctrl:1
	v_rcp_f32_e32 v104, v104
	v_rcp_f32_e32 v105, v105
	v_cndmask_b32_e64 v113, v113, v144, s[6:7]
	v_pk_fma_f32 v[66:67], v[66:67], v[90:91], v[94:95]
	v_pk_fma_f32 v[64:65], v[68:69], v[108:109], v[64:65]
	v_pk_fma_f32 v[66:67], v[86:87], v[112:113], v[66:67]
	v_pk_mul_f32 v[104:105], v[128:129], v[104:105]
	v_pk_fma_f32 v[66:67], v[70:71], v[114:115], v[66:67]
	v_lshlrev_b32_e32 v100, 1, v175
	v_mov_b32_e32 v101, v19
	v_pk_mul_f32 v[64:65], v[104:105], v[64:65]
	s_nop 0
	v_cvt_pk_bf16_f32 v150, v64, v65
	v_mul_f32_e32 v64, 0xbfb8aa3b, v130
	v_mul_f32_e32 v65, 0xbfb8aa3b, v131
	v_exp_f32_e32 v64, v64
	v_exp_f32_e32 v65, v65
	v_add_f32_e32 v64, 1.0, v64
	v_add_f32_e32 v65, 1.0, v65
	v_rcp_f32_e32 v64, v64
	v_rcp_f32_e32 v65, v65
	s_nop 0
	v_pk_mul_f32 v[64:65], v[130:131], v[64:65]
	s_nop 0
	v_pk_mul_f32 v[64:65], v[64:65], v[66:67]
	s_nop 0
	v_cvt_pk_bf16_f32 v151, v64, v65
	v_lshl_add_u64 v[64:65], s[70:71], 0, v[18:19]
	v_lshl_add_u64 v[114:115], v[64:65], 0, v[100:101]
	global_store_dwordx4 v[114:115], v[148:151], off
	s_nop 0
	s_nop 0
	s_nop 0
	v_mov_b32_dpp v18, v60 row_shr:1 row_mask:0xf bank_mask:0xf bound_ctrl:1
	v_mov_b32_dpp v65, v60 row_shr:2 row_mask:0xf bank_mask:0xf bound_ctrl:1
	v_mov_b32_dpp v64, v208 row_shl:1 row_mask:0xf bank_mask:0xf bound_ctrl:1
	v_cndmask_b32_e64 v64, v18, v64, s[6:7]
	v_cndmask_b32_e64 v66, v65, v208, s[4:5]
	v_mov_b32_dpp v18, v61 row_shr:1 row_mask:0xf bank_mask:0xf bound_ctrl:1
	v_mov_b32_dpp v65, v209 row_shl:1 row_mask:0xf bank_mask:0xf bound_ctrl:1
	v_cndmask_b32_e64 v65, v18, v65, s[6:7]
	v_mov_b32_dpp v101, v62 row_shr:2 row_mask:0xf bank_mask:0xf
	v_mov_b32_dpp v100, v210 row_shl:1 row_mask:0xf bank_mask:0xf bound_ctrl:1
	v_mov_b32_dpp v18, v62 row_shr:1 row_mask:0xf bank_mask:0xf bound_ctrl:1
	v_cndmask_b32_e64 v100, v18, v100, s[6:7]
	v_cndmask_b32_e64 v104, v101, v210, s[4:5]
	v_mov_b32_dpp v18, v63 row_shr:1 row_mask:0xf bank_mask:0xf bound_ctrl:1
	v_mov_b32_dpp v101, v211 row_shl:1 row_mask:0xf bank_mask:0xf bound_ctrl:1
	v_mov_b32_dpp v67, v61 row_shr:2 row_mask:0xf bank_mask:0xf bound_ctrl:1
; __device__ __forceinline__ unsigned cvt_pk_bf16(float lo, float hi) { const bf16x2_t r = __builtin_convertvector((f32x2){lo, hi}, bf16x2_t); return __builtin_bit_cast(unsigned, r); }
; __device__ __forceinline__ float silu_f(float x) { return x * __builtin_amdgcn_rcpf(1.0f + __expf(-x)); }
;     __device__ __forceinline__ f32x4 conv4s(const f32x4 c4, const f32x4 pv, int t, const f32x4 w0, const f32x4 w1, const f32x4 w2, const f32x4 bsv) const {
;         f32x4 p1, p2;
; #pragma unroll
;         for (int e = 0; e < 4; ++e) { p1[e] = dpp_f<0x111>(0.f, c4[e]); p2[e] = dpp_f<0x112>(0.f, c4[e]); const float q1 = dpp_f<0x101>(0.f, pv[e]);
;             p1[e] = t == 0 ? q1 : p1[e]; p2[e] = t < 2 ? pv[e] : p2[e]; }
;         f32x4 uu = bsv + w2 * c4 + w1 * p1 + w0 * p2;
;         asm volatile("" : "+v"(uu));
;         return uu;
;     __device__ __forceinline__ void sample(f32x4 (&acc)[2][2][4][2], const Unit& u, int row0t, int wr, int wc, int fr, int fq) const {
;     ...
;             for (int k = 0; k < 4; ++k) { pv[k] = (f32x4){0.f, 0.f, 0.f, 0.f}; if (t < 2) pv[k] = *(const f32x4*)((const char*)st + stoff + (unsigned)(((16 * ai + 2 * (mp + k)) * 2 * DFF2 + DFF + 4 * n) * 4)); }
; #pragma unroll
;             for (int k = 0; k < 4; ++k) { const int m = mp + k;
;                 const f32x4 uu = conv4s(acc[ai][1][m][n], pv[k], t, w0, w1, w2, bsv);
;                 const f32x4 ua = acc[ai][0][m][n];
;                 u32x2 w; w.x = cvt_pk_bf16(silu_f(ua[0]) * uu[0], silu_f(ua[1]) * uu[1]); w.y = cvt_pk_bf16(silu_f(ua[2]) * uu[2], silu_f(ua[3]) * uu[3]);
;                 if ((step & 1) == 0) pend[m] = w;
;                 else { u32x4 o; if (n == 1) { o.x = pend[m].x; o.y = pend[m].y; o.z = w.x; o.w = w.y; } else { o.x = w.x; o.y = w.y; o.z = pend[m].x; o.w = pend[m].y; }
;                     *(u32x4*)((char*)act + rowoff0 + (unsigned)((ai * HALF + m * 16) * DFF * 2) + (unsigned)(ca * 2)) = o; }
	v_cndmask_b32_e64 v101, v18, v101, s[6:7]
	v_pk_fma_f32 v[60:61], v[60:61], v[88:89], v[92:93]
	v_mul_f32_e32 v18, 0xbfb8aa3b, v124
	v_pk_fma_f32 v[60:61], v[84:85], v[64:65], v[60:61]
	v_exp_f32_e32 v18, v18
	v_mul_f32_e32 v64, 0xbfb8aa3b, v125
	v_exp_f32_e32 v65, v64
	v_cndmask_b32_e64 v67, v67, v209, s[4:5]
	v_add_f32_e32 v18, 1.0, v18
	v_rcp_f32_e32 v64, v18
	v_add_f32_e32 v18, 1.0, v65
	v_mul_f32_e32 v65, 0xbfb8aa3b, v126
	v_pk_fma_f32 v[60:61], v[68:69], v[66:67], v[60:61]
	v_exp_f32_e32 v66, v65
	v_mul_f32_e32 v65, 0xbfb8aa3b, v127
	v_exp_f32_e32 v67, v65
	s_nop 0
	v_rcp_f32_e32 v65, v18
	v_add_f32_e32 v18, 1.0, v66
	v_mov_b32_dpp v105, v63 row_shr:2 row_mask:0xf bank_mask:0xf bound_ctrl:1
	v_pk_fma_f32 v[62:63], v[62:63], v[90:91], v[94:95]
	v_rcp_f32_e32 v66, v18
	v_add_f32_e32 v18, 1.0, v67
	v_cndmask_b32_e64 v105, v105, v211, s[4:5]
	v_pk_fma_f32 v[62:63], v[86:87], v[100:101], v[62:63]
	v_rcp_f32_e32 v67, v18
	v_pk_fma_f32 v[62:63], v[70:71], v[104:105], v[62:63]
	v_pk_mul_f32 v[64:65], v[124:125], v[64:65]
	s_mov_b32 s2, 0x16000
	v_pk_mul_f32 v[60:61], v[64:65], v[60:61]
	s_nop 0
	v_cvt_pk_bf16_f32 v112, v60, v61
	v_pk_mul_f32 v[60:61], v[126:127], v[66:67]
	s_nop 0
	v_pk_mul_f32 v[60:61], v[60:61], v[62:63]
	s_nop 0
	v_cvt_pk_bf16_f32 v113, v60, v61
	v_add_co_u32_e32 v60, vcc, s2, v114
	s_nop 1
	v_addc_co_u32_e32 v61, vcc, 0, v115, vcc
	global_store_dwordx4 v[60:61], v[110:113], off
	s_nop 0
	s_nop 0
	s_nop 0
	v_mov_b32_dpp v18, v56 row_shr:1 row_mask:0xf bank_mask:0xf bound_ctrl:1
	v_mov_b32_dpp v61, v56 row_shr:2 row_mask:0xf bank_mask:0xf bound_ctrl:1
	v_mov_b32_dpp v60, v212 row_shl:1 row_mask:0xf bank_mask:0xf bound_ctrl:1
	v_cndmask_b32_e64 v60, v18, v60, s[6:7]
	v_cndmask_b32_e64 v62, v61, v212, s[4:5]
	v_mov_b32_dpp v18, v57 row_shr:1 row_mask:0xf bank_mask:0xf bound_ctrl:1
	v_mov_b32_dpp v61, v213 row_shl:1 row_mask:0xf bank_mask:0xf bound_ctrl:1
	v_cndmask_b32_e64 v61, v18, v61, s[6:7]
	v_mov_b32_dpp v65, v58 row_shr:2 row_mask:0xf bank_mask:0xf bound_ctrl:1
	v_mov_b32_dpp v18, v58 row_shr:1 row_mask:0xf bank_mask:0xf bound_ctrl:1
	v_mov_b32_dpp v64, v214 row_shl:1 row_mask:0xf bank_mask:0xf bound_ctrl:1
	v_cndmask_b32_e64 v64, v18, v64, s[6:7]
	v_cndmask_b32_e64 v66, v65, v214, s[4:5]
	v_mov_b32_dpp v18, v59 row_shr:1 row_mask:0xf bank_mask:0xf bound_ctrl:1
	v_mov_b32_dpp v65, v215 row_shl:1 row_mask:0xf bank_mask:0xf bound_ctrl:1
	v_mov_b32_dpp v63, v57 row_shr:2 row_mask:0xf bank_mask:0xf bound_ctrl:1
	v_cndmask_b32_e64 v65, v18, v65, s[6:7]
	v_pk_fma_f32 v[56:57], v[56:57], v[88:89], v[92:93]
	v_mul_f32_e32 v18, 0xbfb8aa3b, v120
	v_pk_fma_f32 v[56:57], v[84:85], v[60:61], v[56:57]
	v_exp_f32_e32 v18, v18
	v_mul_f32_e32 v60, 0xbfb8aa3b, v121
	v_exp_f32_e32 v61, v60
	v_cndmask_b32_e64 v63, v63, v213, s[4:5]
	v_add_f32_e32 v18, 1.0, v18
	v_rcp_f32_e32 v60, v18
	v_add_f32_e32 v18, 1.0, v61
	v_mul_f32_e32 v61, 0xbfb8aa3b, v122
	v_pk_fma_f32 v[56:57], v[68:69], v[62:63], v[56:57]
	v_exp_f32_e32 v62, v61
	v_mul_f32_e32 v61, 0xbfb8aa3b, v123
	v_exp_f32_e32 v63, v61
	s_nop 0
	v_rcp_f32_e32 v61, v18
	v_add_f32_e32 v18, 1.0, v62
	v_mov_b32_dpp v67, v59 row_shr:2 row_mask:0xf bank_mask:0xf bound_ctrl:1
	v_pk_fma_f32 v[58:59], v[58:59], v[90:91], v[94:95]
	v_rcp_f32_e32 v62, v18
	v_add_f32_e32 v18, 1.0, v63
	v_cndmask_b32_e64 v67, v67, v215, s[4:5]
	v_pk_fma_f32 v[58:59], v[86:87], v[64:65], v[58:59]
	v_rcp_f32_e32 v63, v18
	v_pk_fma_f32 v[58:59], v[70:71], v[66:67], v[58:59]
	v_pk_mul_f32 v[60:61], v[120:121], v[60:61]
	s_mov_b32 s2, 0x2c000
	v_pk_mul_f32 v[56:57], v[60:61], v[56:57]
	s_nop 0
	v_cvt_pk_bf16_f32 v108, v56, v57
	v_pk_mul_f32 v[56:57], v[122:123], v[62:63]
	s_nop 0
	v_pk_mul_f32 v[56:57], v[56:57], v[58:59]
	s_nop 0
	v_cvt_pk_bf16_f32 v109, v56, v57
	v_add_co_u32_e32 v56, vcc, s2, v114
	s_nop 1
	v_addc_co_u32_e32 v57, vcc, 0, v115, vcc
	global_store_dwordx4 v[56:57], v[106:109], off
	s_nop 0
	s_nop 0
	s_nop 0
	v_mov_b32_dpp v18, v32 row_shr:1 row_mask:0xf bank_mask:0xf bound_ctrl:1
	v_mov_b32_dpp v57, v32 row_shr:2 row_mask:0xf bank_mask:0xf bound_ctrl:1
	v_mov_b32_dpp v56, v216 row_shl:1 row_mask:0xf bank_mask:0xf bound_ctrl:1
	v_cndmask_b32_e64 v56, v18, v56, s[6:7]
	v_cndmask_b32_e64 v58, v57, v216, s[4:5]
	v_mov_b32_dpp v18, v33 row_shr:1 row_mask:0xf bank_mask:0xf bound_ctrl:1
	v_mov_b32_dpp v57, v217 row_shl:1 row_mask:0xf bank_mask:0xf bound_ctrl:1
	v_cndmask_b32_e64 v57, v18, v57, s[6:7]
	v_mov_b32_dpp v61, v34 row_shr:2 row_mask:0xf bank_mask:0xf bound_ctrl:1
	v_mov_b32_dpp v18, v34 row_shr:1 row_mask:0xf bank_mask:0xf bound_ctrl:1
	v_mov_b32_dpp v60, v218 row_shl:1 row_mask:0xf bank_mask:0xf bound_ctrl:1
	v_cndmask_b32_e64 v60, v18, v60, s[6:7]
	v_cndmask_b32_e64 v62, v61, v218, s[4:5]
	v_mov_b32_dpp v18, v35 row_shr:1 row_mask:0xf bank_mask:0xf bound_ctrl:1
	v_mov_b32_dpp v61, v219 row_shl:1 row_mask:0xf bank_mask:0xf bound_ctrl:1
	v_mov_b32_dpp v59, v33 row_shr:2 row_mask:0xf bank_mask:0xf bound_ctrl:1
	v_cndmask_b32_e64 v61, v18, v61, s[6:7]
	v_pk_fma_f32 v[32:33], v[32:33], v[88:89], v[92:93]
	v_mul_f32_e32 v18, 0xbfb8aa3b, v116
	v_pk_fma_f32 v[32:33], v[84:85], v[56:57], v[32:33]
	v_exp_f32_e32 v18, v18
	v_mul_f32_e32 v56, 0xbfb8aa3b, v117
	v_exp_f32_e32 v57, v56
	v_cndmask_b32_e64 v59, v59, v217, s[4:5]
	v_add_f32_e32 v18, 1.0, v18
	v_rcp_f32_e32 v56, v18
	v_add_f32_e32 v18, 1.0, v57
	v_mul_f32_e32 v57, 0xbfb8aa3b, v118
	v_pk_fma_f32 v[32:33], v[68:69], v[58:59], v[32:33]
	v_exp_f32_e32 v58, v57
	v_mul_f32_e32 v57, 0xbfb8aa3b, v119
	v_exp_f32_e32 v59, v57
	s_nop 0
	v_rcp_f32_e32 v57, v18
	v_add_f32_e32 v18, 1.0, v58
	v_mov_b32_dpp v63, v35 row_shr:2 row_mask:0xf bank_mask:0xf bound_ctrl:1
	v_pk_fma_f32 v[34:35], v[34:35], v[90:91], v[94:95]
	v_rcp_f32_e32 v58, v18
	v_add_f32_e32 v18, 1.0, v59
	v_cndmask_b32_e64 v63, v63, v219, s[4:5]
	v_pk_fma_f32 v[34:35], v[86:87], v[60:61], v[34:35]
	v_rcp_f32_e32 v59, v18
	v_pk_fma_f32 v[34:35], v[70:71], v[62:63], v[34:35]
	v_pk_mul_f32 v[56:57], v[116:117], v[56:57]
	s_nop 0
	v_pk_mul_f32 v[32:33], v[56:57], v[32:33]
	s_nop 0
	v_cvt_pk_bf16_f32 v104, v32, v33
	v_pk_mul_f32 v[32:33], v[118:119], v[58:59]
	s_nop 0
	v_pk_mul_f32 v[32:33], v[32:33], v[34:35]
	s_nop 0
	v_cvt_pk_bf16_f32 v105, v32, v33
	v_add_co_u32_e32 v32, vcc, 0x42000, v114
	s_nop 1
	v_addc_co_u32_e32 v33, vcc, 0, v115, vcc
	global_store_dwordx4 v[32:33], v[102:105], off
	v_mov_b32_e32 v56, 0
	v_mov_b32_e32 v64, 0
	v_mov_b32_e32 v65, 0
	v_mov_b32_e32 v66, 0
	v_mov_b32_e32 v67, 0
	v_mov_b32_e32 v57, 0
	v_mov_b32_e32 v58, 0
	v_mov_b32_e32 v59, 0
	v_mov_b32_e32 v32, 0
	v_mov_b32_e32 v60, 0
	v_mov_b32_e32 v61, 0
	v_mov_b32_e32 v62, 0
	v_mov_b32_e32 v63, 0
	v_mov_b32_e32 v33, 0
	v_mov_b32_e32 v34, 0
	v_mov_b32_e32 v35, 0
	s_nop 0
	s_nop 0
	v_mov_b32_e32 v100, v19
	v_mov_b32_dpp v18, v52 row_shr:1 row_mask:0xf bank_mask:0xf bound_ctrl:1
	v_mov_b32_dpp v101, v52 row_shr:2 row_mask:0xf bank_mask:0xf bound_ctrl:1
	s_waitcnt vmcnt(0)
; __device__ __forceinline__ unsigned cvt_pk_bf16(float lo, float hi) { const bf16x2_t r = __builtin_convertvector((f32x2){lo, hi}, bf16x2_t); return __builtin_bit_cast(unsigned, r); }
; __device__ __forceinline__ float silu_f(float x) { return x * __builtin_amdgcn_rcpf(1.0f + __expf(-x)); }
;     __device__ __forceinline__ f32x4 conv4s(const f32x4 c4, const f32x4 pv, int t, const f32x4 w0, const f32x4 w1, const f32x4 w2, const f32x4 bsv) const {
;         f32x4 p1, p2;
; #pragma unroll
;         for (int e = 0; e < 4; ++e) { p1[e] = dpp_f<0x111>(0.f, c4[e]); p2[e] = dpp_f<0x112>(0.f, c4[e]); const float q1 = dpp_f<0x101>(0.f, pv[e]);
;             p1[e] = t == 0 ? q1 : p1[e]; p2[e] = t < 2 ? pv[e] : p2[e]; }
;         f32x4 uu = bsv + w2 * c4 + w1 * p1 + w0 * p2;
;         asm volatile("" : "+v"(uu));
;         return uu;
;     __device__ __forceinline__ void sample(f32x4 (&acc)[2][2][4][2], const Unit& u, int row0t, int wr, int wc, int fr, int fq) const {
;     ...
;             for (int mp = 0; mp < 4; mp += 4) {
;             f32x4 pv[4];
; #pragma unroll
;             for (int k = 0; k < 4; ++k) { pv[k] = (f32x4){0.f, 0.f, 0.f, 0.f}; if (t < 2) pv[k] = *(const f32x4*)((const char*)st + stoff + (unsigned)(((16 * ai + 2 * (mp + k)) * 2 * DFF2 + DFF + 4 * n) * 4)); }
; #pragma unroll
;             for (int k = 0; k < 4; ++k) { const int m = mp + k;
;                 const f32x4 uu = conv4s(acc[ai][1][m][n], pv[k], t, w0, w1, w2, bsv);
;                 const f32x4 ua = acc[ai][0][m][n];
;                 u32x2 w; w.x = cvt_pk_bf16(silu_f(ua[0]) * uu[0], silu_f(ua[1]) * uu[1]); w.y = cvt_pk_bf16(silu_f(ua[2]) * uu[2], silu_f(ua[3]) * uu[3]);
;                 if ((step & 1) == 0) pend[m] = w;
;                 else { u32x4 o; if (n == 1) { o.x = pend[m].x; o.y = pend[m].y; o.z = w.x; o.w = w.y; } else { o.x = w.x; o.y = w.y; o.z = pend[m].x; o.w = pend[m].y; }
;                     *(u32x4*)((char*)act + rowoff0 + (unsigned)((ai * HALF + m * 16) * DFF * 2) + (unsigned)(ca * 2)) = o; }
	v_mov_b32_e32 v204, 0
	v_mov_b32_e32 v205, 0
	v_mov_b32_e32 v206, 0
	v_mov_b32_e32 v207, 0
	v_mov_b32_e32 v208, 0
	v_mov_b32_e32 v209, 0
	v_mov_b32_e32 v210, 0
	v_mov_b32_e32 v211, 0
	v_mov_b32_e32 v212, 0
	v_mov_b32_e32 v213, 0
	v_mov_b32_e32 v214, 0
	v_mov_b32_e32 v215, 0
	v_mov_b32_e32 v216, 0
	v_mov_b32_e32 v217, 0
	v_mov_b32_e32 v218, 0
	v_mov_b32_e32 v219, 0
	s_and_saveexec_b64 s[100:101], s[4:5]
	s_cbranch_execz .Lspp_7
	s_mov_b64 s[98:99], 0xb2c00
	v_lshl_add_u64 v[194:195], v[172:173], 0, s[98:99]
	global_load_dwordx4 v[204:207], v[194:195], off
	s_mov_b64 s[98:99], 0xc8c00
	v_lshl_add_u64 v[194:195], v[172:173], 0, s[98:99]
	global_load_dwordx4 v[208:211], v[194:195], off
	s_mov_b64 s[98:99], 0xdec00
	v_lshl_add_u64 v[194:195], v[172:173], 0, s[98:99]
	global_load_dwordx4 v[212:215], v[194:195], off
	s_mov_b64 s[98:99], 0xf4c00
	v_lshl_add_u64 v[194:195], v[172:173], 0, s[98:99]
	global_load_dwordx4 v[216:219], v[194:195], off
.Lspp_7:
	s_or_b64 exec, exec, s[100:101]
	s_nop 4
	v_mov_b32_dpp v100, v178 row_shl:1 row_mask:0xf bank_mask:0xf
	v_cndmask_b32_e64 v100, v18, v100, s[6:7]
	v_cndmask_b32_e64 v64, v101, v178, s[4:5]
	s_nop 0
	s_nop 0
	v_mov_b32_dpp v18, v53 row_shr:1 row_mask:0xf bank_mask:0xf bound_ctrl:1
	v_mov_b32_dpp v102, v53 row_shr:2 row_mask:0xf bank_mask:0xf bound_ctrl:1
	v_mov_b32_dpp v101, v179 row_shl:1 row_mask:0xf bank_mask:0xf bound_ctrl:1
	v_cndmask_b32_e64 v101, v18, v101, s[6:7]
	v_cndmask_b32_e64 v65, v102, v179, s[4:5]
	v_mov_b32_dpp v18, v54 row_shr:1 row_mask:0xf bank_mask:0xf bound_ctrl:1
	v_mov_b32_dpp v103, v54 row_shr:2 row_mask:0xf bank_mask:0xf bound_ctrl:1
	v_mov_b32_dpp v102, v180 row_shl:1 row_mask:0xf bank_mask:0xf bound_ctrl:1
	v_cndmask_b32_e64 v102, v18, v102, s[6:7]
	v_cndmask_b32_e64 v66, v103, v180, s[4:5]
	v_mov_b32_dpp v18, v55 row_shr:1 row_mask:0xf bank_mask:0xf bound_ctrl:1
	v_mov_b32_dpp v103, v181 row_shl:1 row_mask:0xf bank_mask:0xf bound_ctrl:1
	v_mov_b32_dpp v104, v55 row_shr:2 row_mask:0xf bank_mask:0xf bound_ctrl:1
	v_cndmask_b32_e64 v103, v18, v103, s[6:7]
	v_pk_fma_f32 v[54:55], v[54:55], v[90:91], v[94:95]
	v_pk_fma_f32 v[52:53], v[52:53], v[88:89], v[92:93]
	v_cndmask_b32_e64 v67, v104, v181, s[4:5]
	v_pk_fma_f32 v[54:55], v[86:87], v[102:103], v[54:55]
	v_pk_fma_f32 v[52:53], v[84:85], v[100:101], v[52:53]
	v_mov_b32_e32 v171, v19
	v_pk_fma_f32 v[102:103], v[70:71], v[66:67], v[54:55]
	v_pk_fma_f32 v[100:101], v[68:69], v[64:65], v[52:53]
	v_lshl_add_u64 v[112:113], s[96:97], 0, v[170:171]
	v_lshl_add_u64 v[116:117], s[0:1], 0, v[170:171]
	v_lshl_add_u64 v[118:119], s[8:9], 0, v[170:171]
	v_lshl_add_u64 v[120:121], s[66:67], 0, v[170:171]
	v_mov_b32_dpp v18, v48 row_shr:1 row_mask:0xf bank_mask:0xf bound_ctrl:1
	v_mov_b32_dpp v53, v48 row_shr:2 row_mask:0xf bank_mask:0xf bound_ctrl:1
	v_mov_b32_dpp v52, v182 row_shl:1 row_mask:0xf bank_mask:0xf bound_ctrl:1
	v_cndmask_b32_e64 v52, v18, v52, s[6:7]
	v_cndmask_b32_e64 v54, v53, v182, s[4:5]
	v_mov_b32_dpp v18, v49 row_shr:1 row_mask:0xf bank_mask:0xf bound_ctrl:1
	v_mov_b32_dpp v55, v49 row_shr:2 row_mask:0xf bank_mask:0xf bound_ctrl:1
	v_mov_b32_dpp v53, v183 row_shl:1 row_mask:0xf bank_mask:0xf bound_ctrl:1
	v_cndmask_b32_e64 v53, v18, v53, s[6:7]
	v_cndmask_b32_e64 v55, v55, v183, s[4:5]
	v_mov_b32_dpp v18, v50 row_shr:1 row_mask:0xf bank_mask:0xf bound_ctrl:1
	v_mov_b32_dpp v57, v50 row_shr:2 row_mask:0xf bank_mask:0xf bound_ctrl:1
	v_mov_b32_dpp v56, v184 row_shl:1 row_mask:0xf bank_mask:0xf bound_ctrl:1
	v_cndmask_b32_e64 v56, v18, v56, s[6:7]
	v_cndmask_b32_e64 v58, v57, v184, s[4:5]
	v_mov_b32_dpp v18, v51 row_shr:1 row_mask:0xf bank_mask:0xf bound_ctrl:1
	v_mov_b32_dpp v57, v185 row_shl:1 row_mask:0xf bank_mask:0xf bound_ctrl:1
	v_mov_b32_dpp v64, v51 row_shr:2 row_mask:0xf bank_mask:0xf bound_ctrl:1
	v_cndmask_b32_e64 v57, v18, v57, s[6:7]
	v_pk_fma_f32 v[50:51], v[50:51], v[90:91], v[94:95]
	v_pk_fma_f32 v[48:49], v[48:49], v[88:89], v[92:93]
	v_cndmask_b32_e64 v59, v64, v185, s[4:5]
	v_pk_fma_f32 v[50:51], v[86:87], v[56:57], v[50:51]
	v_pk_fma_f32 v[48:49], v[84:85], v[52:53], v[48:49]
	v_pk_fma_f32 v[106:107], v[70:71], v[58:59], v[50:51]
	v_pk_fma_f32 v[104:105], v[68:69], v[54:55], v[48:49]
	s_nop 0
	v_mov_b32_dpp v18, v44 row_shr:1 row_mask:0xf bank_mask:0xf bound_ctrl:1
	v_mov_b32_dpp v49, v44 row_shr:2 row_mask:0xf bank_mask:0xf bound_ctrl:1
	v_mov_b32_dpp v48, v186 row_shl:1 row_mask:0xf bank_mask:0xf bound_ctrl:1
	v_cndmask_b32_e64 v48, v18, v48, s[6:7]
	v_cndmask_b32_e64 v50, v49, v186, s[4:5]
	v_mov_b32_dpp v18, v45 row_shr:1 row_mask:0xf bank_mask:0xf bound_ctrl:1
	v_mov_b32_dpp v49, v187 row_shl:1 row_mask:0xf bank_mask:0xf bound_ctrl:1
	v_cndmask_b32_e64 v49, v18, v49, s[6:7]
	v_mov_b32_dpp v53, v46 row_shr:2 row_mask:0xf bank_mask:0xf bound_ctrl:1
	v_mov_b32_dpp v18, v46 row_shr:1 row_mask:0xf bank_mask:0xf bound_ctrl:1
	v_mov_b32_dpp v52, v188 row_shl:1 row_mask:0xf bank_mask:0xf bound_ctrl:1
	v_cndmask_b32_e64 v52, v18, v52, s[6:7]
	v_cndmask_b32_e64 v54, v53, v188, s[4:5]
	v_mov_b32_dpp v18, v47 row_shr:1 row_mask:0xf bank_mask:0xf bound_ctrl:1
	v_mov_b32_dpp v53, v189 row_shl:1 row_mask:0xf bank_mask:0xf bound_ctrl:1
	v_mov_b32_dpp v51, v45 row_shr:2 row_mask:0xf bank_mask:0xf bound_ctrl:1
	v_mov_b32_dpp v55, v47 row_shr:2 row_mask:0xf bank_mask:0xf bound_ctrl:1
	v_cndmask_b32_e64 v53, v18, v53, s[6:7]
	v_pk_fma_f32 v[46:47], v[46:47], v[90:91], v[94:95]
	v_pk_fma_f32 v[44:45], v[44:45], v[88:89], v[92:93]
	v_cndmask_b32_e64 v51, v51, v187, s[4:5]
	v_cndmask_b32_e64 v55, v55, v189, s[4:5]
	v_pk_fma_f32 v[46:47], v[86:87], v[52:53], v[46:47]
	v_pk_fma_f32 v[44:45], v[84:85], v[48:49], v[44:45]
; __device__ __forceinline__ unsigned cvt_pk_bf16(float lo, float hi) { const bf16x2_t r = __builtin_convertvector((f32x2){lo, hi}, bf16x2_t); return __builtin_bit_cast(unsigned, r); }
;     __device__ __forceinline__ f32x4 conv4s(const f32x4 c4, const f32x4 pv, int t, const f32x4 w0, const f32x4 w1, const f32x4 w2, const f32x4 bsv) const {
;         f32x4 p1, p2;
; #pragma unroll
;         for (int e = 0; e < 4; ++e) { p1[e] = dpp_f<0x111>(0.f, c4[e]); p2[e] = dpp_f<0x112>(0.f, c4[e]); const float q1 = dpp_f<0x101>(0.f, pv[e]);
;             p1[e] = t == 0 ? q1 : p1[e]; p2[e] = t < 2 ? pv[e] : p2[e]; }
;         f32x4 uu = bsv + w2 * c4 + w1 * p1 + w0 * p2;
;         asm volatile("" : "+v"(uu));
;         return uu;
;     __device__ __forceinline__ void sample(f32x4 (&acc)[2][2][4][2], const Unit& u, int row0t, int wr, int wc, int fr, int fq) const {
;     ...
;             if (step != 2) { const unsigned cso = (unsigned)((DFF + ca + 4 * n) * 4);
;                 w0 = *(const f32x4*)((const char*)cw + cso); w1 = *(const f32x4*)((const char*)(cw + DFF2) + cso); w2 = *(const f32x4*)((const char*)(cw + 2 * DFF2) + cso); bsv = *(const f32x4*)((const char*)cb + cso);
;                 wk[0] = w0; wk[1] = w1; wk[2] = w2; wk[3] = bsv; }
;             else { w0 = wk[0]; w1 = wk[1]; w2 = wk[2]; bsv = wk[3]; }
; #pragma unroll
;             for (int mp = 0; mp < 4; mp += 4) {
;             f32x4 pv[4];
; #pragma unroll
;             for (int k = 0; k < 4; ++k) { pv[k] = (f32x4){0.f, 0.f, 0.f, 0.f}; if (t < 2) pv[k] = *(const f32x4*)((const char*)st + stoff + (unsigned)(((16 * ai + 2 * (mp + k)) * 2 * DFF2 + DFF + 4 * n) * 4)); }
; #pragma unroll
;             for (int k = 0; k < 4; ++k) { const int m = mp + k;
;                 const f32x4 uu = conv4s(acc[ai][1][m][n], pv[k], t, w0, w1, w2, bsv);
;                 const f32x4 ua = acc[ai][0][m][n];
;                 u32x2 w; w.x = cvt_pk_bf16(silu_f(ua[0]) * uu[0], silu_f(ua[1]) * uu[1]); w.y = cvt_pk_bf16(silu_f(ua[2]) * uu[2], silu_f(ua[3]) * uu[3]);
;                 if ((step & 1) == 0) pend[m] = w;
;                 else { u32x4 o; if (n == 1) { o.x = pend[m].x; o.y = pend[m].y; o.z = w.x; o.w = w.y; } else { o.x = w.x; o.y = w.y; o.z = pend[m].x; o.w = pend[m].y; }
;                     *(u32x4*)((char*)act + rowoff0 + (unsigned)((ai * HALF + m * 16) * DFF * 2) + (unsigned)(ca * 2)) = o; }
	v_pk_fma_f32 v[110:111], v[70:71], v[54:55], v[46:47]
	v_pk_fma_f32 v[108:109], v[68:69], v[50:51], v[44:45]
	s_nop 0
	v_mov_b32_dpp v18, v20 row_shr:1 row_mask:0xf bank_mask:0xf bound_ctrl:1
	v_mov_b32_dpp v45, v20 row_shr:2 row_mask:0xf bank_mask:0xf bound_ctrl:1
	v_mov_b32_dpp v44, v190 row_shl:1 row_mask:0xf bank_mask:0xf bound_ctrl:1
	v_cndmask_b32_e64 v44, v18, v44, s[6:7]
	v_cndmask_b32_e64 v32, v45, v190, s[4:5]
	v_mov_b32_dpp v18, v21 row_shr:1 row_mask:0xf bank_mask:0xf bound_ctrl:1
	v_mov_b32_dpp v46, v21 row_shr:2 row_mask:0xf bank_mask:0xf bound_ctrl:1
	v_mov_b32_dpp v45, v191 row_shl:1 row_mask:0xf bank_mask:0xf bound_ctrl:1
	v_cndmask_b32_e64 v45, v18, v45, s[6:7]
	v_cndmask_b32_e64 v33, v46, v191, s[4:5]
	v_mov_b32_dpp v18, v22 row_shr:1 row_mask:0xf bank_mask:0xf bound_ctrl:1
	v_mov_b32_dpp v47, v22 row_shr:2 row_mask:0xf bank_mask:0xf bound_ctrl:1
	v_mov_b32_dpp v46, v192 row_shl:1 row_mask:0xf bank_mask:0xf bound_ctrl:1
	v_cndmask_b32_e64 v46, v18, v46, s[6:7]
	v_cndmask_b32_e64 v34, v47, v192, s[4:5]
	v_mov_b32_dpp v18, v23 row_shr:1 row_mask:0xf bank_mask:0xf bound_ctrl:1
	v_mov_b32_dpp v47, v193 row_shl:1 row_mask:0xf bank_mask:0xf bound_ctrl:1
	v_mov_b32_dpp v48, v23 row_shr:2 row_mask:0xf bank_mask:0xf bound_ctrl:1
	v_cndmask_b32_e64 v47, v18, v47, s[6:7]
	v_pk_fma_f32 v[22:23], v[22:23], v[90:91], v[94:95]
	v_pk_fma_f32 v[20:21], v[20:21], v[88:89], v[92:93]
	v_cndmask_b32_e64 v35, v48, v193, s[4:5]
	v_pk_fma_f32 v[22:23], v[86:87], v[46:47], v[22:23]
	v_pk_fma_f32 v[20:21], v[84:85], v[44:45], v[20:21]
	v_pk_fma_f32 v[86:87], v[70:71], v[34:35], v[22:23]
	v_pk_fma_f32 v[84:85], v[68:69], v[32:33], v[20:21]
	s_nop 0
	global_load_dwordx4 v[20:23], v[112:113], off
	global_load_dwordx4 v[32:35], v[116:117], off
	global_load_dwordx4 v[44:47], v[118:119], off
	global_load_dwordx4 v[48:51], v[120:121], off
	v_mov_b32_e32 v62, 0
	v_mov_b32_e32 v68, 0
	v_mov_b32_e32 v69, 0
	v_mov_b32_e32 v70, 0
	v_mov_b32_e32 v71, 0
	v_mov_b32_e32 v63, 0
	v_mov_b32_e32 v64, 0
	v_mov_b32_e32 v65, 0
	v_writelane_b32 v244, s50, 58
	s_nop 1
	v_writelane_b32 v244, s51, 59
	v_mov_b32_e32 v52, 0
	v_mov_b32_e32 v58, 0
	v_mov_b32_e32 v59, 0
	v_mov_b32_e32 v60, 0
	v_mov_b32_e32 v61, 0
	v_mov_b32_e32 v53, 0
	v_mov_b32_e32 v54, 0
	v_mov_b32_e32 v55, 0
	v_mul_f32_e32 v18, 0xbfb8aa3b, v96
	v_exp_f32_e32 v18, v18
	s_mov_b32 s0, 0xb0000
	v_add_f32_e32 v18, 1.0, v18
	v_rcp_f32_e32 v56, v18
	v_mul_f32_e32 v18, 0xbfb8aa3b, v97
	v_exp_f32_e32 v18, v18
	s_nop 0
	v_add_f32_e32 v18, 1.0, v18
	v_rcp_f32_e32 v57, v18
	v_mul_f32_e32 v18, 0xbfb8aa3b, v98
	v_exp_f32_e32 v18, v18
	v_pk_mul_f32 v[56:57], v[96:97], v[56:57]
	s_nop 0
	v_pk_mul_f32 v[56:57], v[56:57], v[84:85]
	v_add_f32_e32 v18, 1.0, v18
	v_rcp_f32_e32 v66, v18
	v_mul_f32_e32 v18, 0xbfb8aa3b, v99
	v_exp_f32_e32 v18, v18
	v_cvt_pk_bf16_f32 v56, v56, v57
	v_add_f32_e32 v18, 1.0, v18
	v_rcp_f32_e32 v67, v18
	v_mul_f32_e32 v18, 0xbfb8aa3b, v80
	v_exp_f32_e32 v18, v18
	v_pk_mul_f32 v[66:67], v[98:99], v[66:67]
	s_nop 0
	v_pk_mul_f32 v[66:67], v[66:67], v[86:87]
	v_add_f32_e32 v18, 1.0, v18
	v_cvt_pk_bf16_f32 v57, v66, v67
	v_rcp_f32_e32 v66, v18
	v_mul_f32_e32 v18, 0xbfb8aa3b, v81
	v_exp_f32_e32 v18, v18
	s_nop 0
	v_add_f32_e32 v18, 1.0, v18
	v_rcp_f32_e32 v67, v18
	v_mul_f32_e32 v18, 0xbfb8aa3b, v82
	v_exp_f32_e32 v18, v18
	v_pk_mul_f32 v[66:67], v[80:81], v[66:67]
	s_nop 0
	v_pk_mul_f32 v[66:67], v[66:67], v[108:109]
	v_add_f32_e32 v18, 1.0, v18
	v_rcp_f32_e32 v80, v18
	v_mul_f32_e32 v18, 0xbfb8aa3b, v83
	v_exp_f32_e32 v18, v18
	v_cvt_pk_bf16_f32 v66, v66, v67
	v_add_f32_e32 v18, 1.0, v18
	v_rcp_f32_e32 v81, v18
	v_mul_f32_e32 v18, 0xbfb8aa3b, v76
	v_exp_f32_e32 v18, v18
	v_pk_mul_f32 v[80:81], v[82:83], v[80:81]
	s_nop 0
	v_pk_mul_f32 v[80:81], v[80:81], v[110:111]
	v_add_f32_e32 v18, 1.0, v18
	v_cvt_pk_bf16_f32 v67, v80, v81
	v_rcp_f32_e32 v80, v18
	v_mul_f32_e32 v18, 0xbfb8aa3b, v77
	v_exp_f32_e32 v18, v18
	s_nop 0
	v_add_f32_e32 v18, 1.0, v18
	v_rcp_f32_e32 v81, v18
	v_mul_f32_e32 v18, 0xbfb8aa3b, v78
	v_exp_f32_e32 v18, v18
	v_pk_mul_f32 v[76:77], v[76:77], v[80:81]
	s_nop 0
	v_pk_mul_f32 v[76:77], v[76:77], v[104:105]
	v_add_f32_e32 v18, 1.0, v18
	v_rcp_f32_e32 v80, v18
	v_mul_f32_e32 v18, 0xbfb8aa3b, v79
	v_exp_f32_e32 v18, v18
	v_cvt_pk_bf16_f32 v76, v76, v77
	v_add_f32_e32 v18, 1.0, v18
	v_rcp_f32_e32 v81, v18
	v_mul_f32_e32 v18, 0xbfb8aa3b, v72
	v_exp_f32_e32 v18, v18
	v_pk_mul_f32 v[78:79], v[78:79], v[80:81]
	s_nop 0
	v_pk_mul_f32 v[78:79], v[78:79], v[106:107]
	v_add_f32_e32 v18, 1.0, v18
	v_cvt_pk_bf16_f32 v77, v78, v79
	v_rcp_f32_e32 v78, v18
	v_mul_f32_e32 v18, 0xbfb8aa3b, v73
	v_exp_f32_e32 v18, v18
	s_nop 0
	v_add_f32_e32 v18, 1.0, v18
	v_rcp_f32_e32 v79, v18
	v_mul_f32_e32 v18, 0xbfb8aa3b, v74
	v_exp_f32_e32 v18, v18
	v_mov_b32_dpp v80, v17 row_shr:2 row_mask:0xf bank_mask:0xf bound_ctrl:1
	v_pk_mul_f32 v[72:73], v[72:73], v[78:79]
	v_add_f32_e32 v18, 1.0, v18
	v_rcp_f32_e32 v78, v18
	v_mul_f32_e32 v18, 0xbfb8aa3b, v75
	v_exp_f32_e32 v18, v18
	v_pk_mul_f32 v[72:73], v[72:73], v[100:101]
	v_add_f32_e32 v18, 1.0, v18
	v_rcp_f32_e32 v79, v18
	v_cvt_pk_bf16_f32 v72, v72, v73
	s_nop 0
	v_pk_mul_f32 v[74:75], v[74:75], v[78:79]
	s_nop 0
	v_pk_mul_f32 v[74:75], v[74:75], v[102:103]
	v_mov_b32_dpp v18, v14 row_shr:1 row_mask:0xf bank_mask:0xf bound_ctrl:1
	v_cvt_pk_bf16_f32 v73, v74, v75
	s_nop 0
	s_nop 0
	s_nop 0
	v_mov_b32_dpp v75, v14 row_shr:2 row_mask:0xf bank_mask:0xf bound_ctrl:1
	s_waitcnt vmcnt(0)
; __device__ __forceinline__ unsigned cvt_pk_bf16(float lo, float hi) { const bf16x2_t r = __builtin_convertvector((f32x2){lo, hi}, bf16x2_t); return __builtin_bit_cast(unsigned, r); }
; __device__ __forceinline__ float silu_f(float x) { return x * __builtin_amdgcn_rcpf(1.0f + __expf(-x)); }
;     __device__ __forceinline__ f32x4 conv4s(const f32x4 c4, const f32x4 pv, int t, const f32x4 w0, const f32x4 w1, const f32x4 w2, const f32x4 bsv) const {
;         f32x4 p1, p2;
; #pragma unroll
;         for (int e = 0; e < 4; ++e) { p1[e] = dpp_f<0x111>(0.f, c4[e]); p2[e] = dpp_f<0x112>(0.f, c4[e]); const float q1 = dpp_f<0x101>(0.f, pv[e]);
;             p1[e] = t == 0 ? q1 : p1[e]; p2[e] = t < 2 ? pv[e] : p2[e]; }
;         f32x4 uu = bsv + w2 * c4 + w1 * p1 + w0 * p2;
;         asm volatile("" : "+v"(uu));
;         return uu;
;     __device__ __forceinline__ void sample(f32x4 (&acc)[2][2][4][2], const Unit& u, int row0t, int wr, int wc, int fr, int fq) const {
;     ...
;             for (int k = 0; k < 4; ++k) { pv[k] = (f32x4){0.f, 0.f, 0.f, 0.f}; if (t < 2) pv[k] = *(const f32x4*)((const char*)st + stoff + (unsigned)(((16 * ai + 2 * (mp + k)) * 2 * DFF2 + DFF + 4 * n) * 4)); }
; #pragma unroll
;             for (int k = 0; k < 4; ++k) { const int m = mp + k;
;                 const f32x4 uu = conv4s(acc[ai][1][m][n], pv[k], t, w0, w1, w2, bsv);
;                 const f32x4 ua = acc[ai][0][m][n];
;                 u32x2 w; w.x = cvt_pk_bf16(silu_f(ua[0]) * uu[0], silu_f(ua[1]) * uu[1]); w.y = cvt_pk_bf16(silu_f(ua[2]) * uu[2], silu_f(ua[3]) * uu[3]);
;                 if ((step & 1) == 0) pend[m] = w;
;                 else { u32x4 o; if (n == 1) { o.x = pend[m].x; o.y = pend[m].y; o.z = w.x; o.w = w.y; } else { o.x = w.x; o.y = w.y; o.z = pend[m].x; o.w = pend[m].y; }
;                     *(u32x4*)((char*)act + rowoff0 + (unsigned)((ai * HALF + m * 16) * DFF * 2) + (unsigned)(ca * 2)) = o; }
;                 __builtin_amdgcn_sched_barrier(0);
	v_mov_b32_dpp v74, v204 row_shl:1 row_mask:0xf bank_mask:0xf bound_ctrl:1
	v_cndmask_b32_e64 v74, v18, v74, s[6:7]
	v_cndmask_b32_e64 v68, v75, v204, s[4:5]
	s_nop 0
	s_nop 0
	v_mov_b32_dpp v78, v15 row_shr:2 row_mask:0xf bank_mask:0xf bound_ctrl:1
	v_mov_b32_dpp v18, v15 row_shr:1 row_mask:0xf bank_mask:0xf bound_ctrl:1
	v_mov_b32_dpp v75, v205 row_shl:1 row_mask:0xf bank_mask:0xf bound_ctrl:1
	v_cndmask_b32_e64 v75, v18, v75, s[6:7]
	v_cndmask_b32_e64 v69, v78, v205, s[4:5]
	v_mov_b32_dpp v18, v16 row_shr:1 row_mask:0xf bank_mask:0xf bound_ctrl:1
	v_mov_b32_dpp v79, v16 row_shr:2 row_mask:0xf bank_mask:0xf bound_ctrl:1
	v_mov_b32_dpp v78, v206 row_shl:1 row_mask:0xf bank_mask:0xf bound_ctrl:1
	v_cndmask_b32_e64 v78, v18, v78, s[6:7]
	v_cndmask_b32_e64 v70, v79, v206, s[4:5]
	s_nop 0
	v_pk_fma_f32 v[14:15], v[14:15], v[44:45], v[48:49]
	v_mov_b32_dpp v18, v17 row_shr:1 row_mask:0xf bank_mask:0xf bound_ctrl:1
	v_mov_b32_dpp v79, v207 row_shl:1 row_mask:0xf bank_mask:0xf bound_ctrl:1
	v_cndmask_b32_e64 v79, v18, v79, s[6:7]
	v_mul_f32_e32 v18, 0xbfb8aa3b, v40
	v_exp_f32_e32 v18, v18
	v_pk_fma_f32 v[14:15], v[32:33], v[74:75], v[14:15]
	v_pk_fma_f32 v[16:17], v[16:17], v[46:47], v[50:51]
	v_pk_fma_f32 v[14:15], v[20:21], v[68:69], v[14:15]
	v_add_f32_e32 v18, 1.0, v18
	v_rcp_f32_e32 v68, v18
	v_mul_f32_e32 v18, 0xbfb8aa3b, v41
	v_exp_f32_e32 v18, v18
	v_cndmask_b32_e64 v71, v80, v207, s[4:5]
	v_pk_fma_f32 v[16:17], v[34:35], v[78:79], v[16:17]
	v_add_f32_e32 v18, 1.0, v18
	v_rcp_f32_e32 v69, v18
	v_pk_fma_f32 v[16:17], v[22:23], v[70:71], v[16:17]
	v_pk_mul_f32 v[40:41], v[40:41], v[68:69]
	s_nop 0
	v_pk_mul_f32 v[14:15], v[40:41], v[14:15]
	s_nop 0
	v_cvt_pk_bf16_f32 v70, v14, v15
	v_mul_f32_e32 v14, 0xbfb8aa3b, v42
	v_mul_f32_e32 v15, 0xbfb8aa3b, v43
	v_exp_f32_e32 v14, v14
	v_exp_f32_e32 v15, v15
	v_add_f32_e32 v14, 1.0, v14
	v_add_f32_e32 v15, 1.0, v15
	v_rcp_f32_e32 v14, v14
	v_rcp_f32_e32 v15, v15
	s_nop 0
	v_pk_mul_f32 v[14:15], v[42:43], v[14:15]
	s_nop 0
	v_pk_mul_f32 v[14:15], v[14:15], v[16:17]
	s_nop 0
	v_cvt_pk_bf16_f32 v71, v14, v15
	v_add_co_u32_e32 v14, vcc, s0, v114
	s_nop 1
	v_addc_co_u32_e32 v15, vcc, 0, v115, vcc
	global_store_dwordx4 v[14:15], v[70:73], off
	s_nop 0
	s_nop 0
	s_nop 0
	v_mov_b32_dpp v14, v10 row_shr:1 row_mask:0xf bank_mask:0xf bound_ctrl:1
	v_mov_b32_dpp v15, v10 row_shr:2 row_mask:0xf bank_mask:0xf bound_ctrl:1
	v_mov_b32_dpp v16, v208 row_shl:1 row_mask:0xf bank_mask:0xf bound_ctrl:1
	v_cndmask_b32_e64 v14, v14, v16, s[6:7]
	v_cndmask_b32_e64 v16, v15, v208, s[4:5]
	v_mov_b32_dpp v15, v11 row_shr:1 row_mask:0xf bank_mask:0xf bound_ctrl:1
	v_mov_b32_dpp v18, v209 row_shl:1 row_mask:0xf bank_mask:0xf bound_ctrl:1
	v_mov_b32_dpp v17, v11 row_shr:2 row_mask:0xf bank_mask:0xf bound_ctrl:1
	v_cndmask_b32_e64 v15, v15, v18, s[6:7]
	v_pk_fma_f32 v[10:11], v[10:11], v[44:45], v[48:49]
	v_cndmask_b32_e64 v17, v17, v209, s[4:5]
	v_pk_fma_f32 v[10:11], v[32:33], v[14:15], v[10:11]
	v_mul_f32_e32 v14, 0xbfb8aa3b, v36
	v_mul_f32_e32 v15, 0xbfb8aa3b, v37
	v_exp_f32_e32 v14, v14
	v_exp_f32_e32 v15, v15
	v_pk_fma_f32 v[10:11], v[20:21], v[16:17], v[10:11]
	v_mul_f32_e32 v16, 0xbfb8aa3b, v38
	v_mul_f32_e32 v17, 0xbfb8aa3b, v39
	s_nop 0
	s_nop 0
	s_nop 0
	v_exp_f32_e32 v16, v16
	v_exp_f32_e32 v17, v17
	v_mov_b32_dpp v18, v12 row_shr:1 row_mask:0xf bank_mask:0xf bound_ctrl:1
	v_mov_b32_dpp v41, v12 row_shr:2 row_mask:0xf bank_mask:0xf bound_ctrl:1
	v_mov_b32_dpp v40, v210 row_shl:1 row_mask:0xf bank_mask:0xf bound_ctrl:1
	v_cndmask_b32_e64 v40, v18, v40, s[6:7]
	v_cndmask_b32_e64 v42, v41, v210, s[4:5]
	s_nop 0
	s_nop 0
	v_add_f32_e32 v14, 1.0, v14
	v_add_f32_e32 v15, 1.0, v15
	v_mov_b32_dpp v18, v13 row_shr:1 row_mask:0xf bank_mask:0xf bound_ctrl:1
	s_nop 0
	v_mov_b32_dpp v41, v211 row_shl:1 row_mask:0xf bank_mask:0xf bound_ctrl:1
	v_rcp_f32_e32 v14, v14
	v_rcp_f32_e32 v15, v15
	v_mov_b32_dpp v43, v13 row_shr:2 row_mask:0xf bank_mask:0xf bound_ctrl:1
	v_cndmask_b32_e64 v41, v18, v41, s[6:7]
	v_pk_fma_f32 v[12:13], v[12:13], v[46:47], v[50:51]
	v_add_f32_e32 v16, 1.0, v16
	v_add_f32_e32 v17, 1.0, v17
	v_cndmask_b32_e64 v43, v43, v211, s[4:5]
	v_pk_fma_f32 v[12:13], v[34:35], v[40:41], v[12:13]
	v_rcp_f32_e32 v16, v16
	v_rcp_f32_e32 v17, v17
	v_pk_fma_f32 v[12:13], v[22:23], v[42:43], v[12:13]
	v_pk_mul_f32 v[14:15], v[36:37], v[14:15]
	s_mov_b32 s0, 0xc6000
	v_pk_mul_f32 v[10:11], v[14:15], v[10:11]
	s_nop 0
	v_cvt_pk_bf16_f32 v74, v10, v11
	v_pk_mul_f32 v[10:11], v[38:39], v[16:17]
	s_nop 0
	v_pk_mul_f32 v[10:11], v[10:11], v[12:13]
	s_nop 0
	v_cvt_pk_bf16_f32 v75, v10, v11
	v_add_co_u32_e32 v10, vcc, s0, v114
	s_nop 1
	v_addc_co_u32_e32 v11, vcc, 0, v115, vcc
	global_store_dwordx4 v[10:11], v[74:77], off
	s_nop 0
	s_nop 0
	s_nop 0
	v_mov_b32_dpp v10, v6 row_shr:1 row_mask:0xf bank_mask:0xf bound_ctrl:1
; __device__ __forceinline__ unsigned cvt_pk_bf16(float lo, float hi) { const bf16x2_t r = __builtin_convertvector((f32x2){lo, hi}, bf16x2_t); return __builtin_bit_cast(unsigned, r); }
; __device__ __forceinline__ float silu_f(float x) { return x * __builtin_amdgcn_rcpf(1.0f + __expf(-x)); }
;     __device__ __forceinline__ void sample(f32x4 (&acc)[2][2][4][2], const Unit& u, int row0t, int wr, int wc, int fr, int fq) const {
;     ...
;             for (int k = 0; k < 4; ++k) { pv[k] = (f32x4){0.f, 0.f, 0.f, 0.f}; if (t < 2) pv[k] = *(const f32x4*)((const char*)st + stoff + (unsigned)(((16 * ai + 2 * (mp + k)) * 2 * DFF2 + DFF + 4 * n) * 4)); }
; #pragma unroll
;             for (int k = 0; k < 4; ++k) { const int m = mp + k;
;                 const f32x4 uu = conv4s(acc[ai][1][m][n], pv[k], t, w0, w1, w2, bsv);
;                 const f32x4 ua = acc[ai][0][m][n];
;                 u32x2 w; w.x = cvt_pk_bf16(silu_f(ua[0]) * uu[0], silu_f(ua[1]) * uu[1]); w.y = cvt_pk_bf16(silu_f(ua[2]) * uu[2], silu_f(ua[3]) * uu[3]);
;                 if ((step & 1) == 0) pend[m] = w;
;                 else { u32x4 o; if (n == 1) { o.x = pend[m].x; o.y = pend[m].y; o.z = w.x; o.w = w.y; } else { o.x = w.x; o.y = w.y; o.z = pend[m].x; o.w = pend[m].y; }
;                     *(u32x4*)((char*)act + rowoff0 + (unsigned)((ai * HALF + m * 16) * DFF * 2) + (unsigned)(ca * 2)) = o; }
;                 __builtin_amdgcn_sched_barrier(0);
	v_mov_b32_dpp v11, v6 row_shr:2 row_mask:0xf bank_mask:0xf bound_ctrl:1
	v_mov_b32_dpp v12, v212 row_shl:1 row_mask:0xf bank_mask:0xf bound_ctrl:1
	v_cndmask_b32_e64 v10, v10, v12, s[6:7]
	v_cndmask_b32_e64 v12, v11, v212, s[4:5]
	v_mov_b32_dpp v11, v7 row_shr:1 row_mask:0xf bank_mask:0xf bound_ctrl:1
	v_mov_b32_dpp v14, v213 row_shl:1 row_mask:0xf bank_mask:0xf bound_ctrl:1
	v_mov_b32_dpp v13, v7 row_shr:2 row_mask:0xf bank_mask:0xf bound_ctrl:1
	v_cndmask_b32_e64 v11, v11, v14, s[6:7]
	v_pk_fma_f32 v[6:7], v[6:7], v[44:45], v[48:49]
	v_cndmask_b32_e64 v13, v13, v213, s[4:5]
	v_pk_fma_f32 v[6:7], v[32:33], v[10:11], v[6:7]
	v_mul_f32_e32 v10, 0xbfb8aa3b, v28
	v_mul_f32_e32 v11, 0xbfb8aa3b, v29
	v_exp_f32_e32 v10, v10
	v_exp_f32_e32 v11, v11
	v_pk_fma_f32 v[6:7], v[20:21], v[12:13], v[6:7]
	v_mul_f32_e32 v12, 0xbfb8aa3b, v30
	v_mul_f32_e32 v13, 0xbfb8aa3b, v31
	s_nop 0
	s_nop 0
	s_nop 0
	v_exp_f32_e32 v12, v12
	v_exp_f32_e32 v13, v13
	v_mov_b32_dpp v14, v8 row_shr:1 row_mask:0xf bank_mask:0xf bound_ctrl:1
	v_mov_b32_dpp v15, v8 row_shr:2 row_mask:0xf bank_mask:0xf bound_ctrl:1
	v_mov_b32_dpp v16, v214 row_shl:1 row_mask:0xf bank_mask:0xf bound_ctrl:1
	v_cndmask_b32_e64 v14, v14, v16, s[6:7]
	v_cndmask_b32_e64 v16, v15, v214, s[4:5]
	s_nop 0
	s_nop 0
	v_add_f32_e32 v10, 1.0, v10
	v_add_f32_e32 v11, 1.0, v11
	v_mov_b32_dpp v15, v9 row_shr:1 row_mask:0xf bank_mask:0xf bound_ctrl:1
	s_nop 0
	v_mov_b32_dpp v18, v215 row_shl:1 row_mask:0xf bank_mask:0xf bound_ctrl:1
	v_rcp_f32_e32 v10, v10
	v_rcp_f32_e32 v11, v11
	v_mov_b32_dpp v17, v9 row_shr:2 row_mask:0xf bank_mask:0xf bound_ctrl:1
	v_cndmask_b32_e64 v15, v15, v18, s[6:7]
	v_pk_fma_f32 v[8:9], v[8:9], v[46:47], v[50:51]
	v_add_f32_e32 v12, 1.0, v12
	v_add_f32_e32 v13, 1.0, v13
	v_cndmask_b32_e64 v17, v17, v215, s[4:5]
	v_pk_fma_f32 v[8:9], v[34:35], v[14:15], v[8:9]
	v_rcp_f32_e32 v12, v12
	v_rcp_f32_e32 v13, v13
	v_pk_fma_f32 v[8:9], v[22:23], v[16:17], v[8:9]
	v_pk_mul_f32 v[10:11], v[28:29], v[10:11]
	s_mov_b32 s0, 0xdc000
	v_pk_mul_f32 v[6:7], v[10:11], v[6:7]
	s_nop 0
	v_cvt_pk_bf16_f32 v64, v6, v7
	v_pk_mul_f32 v[6:7], v[30:31], v[12:13]
	s_nop 0
	v_pk_mul_f32 v[6:7], v[6:7], v[8:9]
	s_nop 0
	v_cvt_pk_bf16_f32 v65, v6, v7
	v_add_co_u32_e32 v6, vcc, s0, v114
	s_nop 1
	v_addc_co_u32_e32 v7, vcc, 0, v115, vcc
	global_store_dwordx4 v[6:7], v[64:67], off
	s_nop 0
	s_nop 0
	s_nop 0
	v_mov_b32_dpp v6, v2 row_shr:1 row_mask:0xf bank_mask:0xf bound_ctrl:1
	v_mov_b32_dpp v7, v2 row_shr:2 row_mask:0xf bank_mask:0xf bound_ctrl:1
	v_mov_b32_dpp v8, v216 row_shl:1 row_mask:0xf bank_mask:0xf bound_ctrl:1
	v_cndmask_b32_e64 v6, v6, v8, s[6:7]
	v_cndmask_b32_e64 v8, v7, v216, s[4:5]
	v_mov_b32_dpp v7, v3 row_shr:1 row_mask:0xf bank_mask:0xf bound_ctrl:1
	v_mov_b32_dpp v10, v217 row_shl:1 row_mask:0xf bank_mask:0xf bound_ctrl:1
	v_mov_b32_dpp v9, v3 row_shr:2 row_mask:0xf bank_mask:0xf bound_ctrl:1
	v_cndmask_b32_e64 v7, v7, v10, s[6:7]
	v_pk_fma_f32 v[2:3], v[2:3], v[44:45], v[48:49]
	v_cndmask_b32_e64 v9, v9, v217, s[4:5]
	v_pk_fma_f32 v[2:3], v[32:33], v[6:7], v[2:3]
	v_mul_f32_e32 v6, 0xbfb8aa3b, v24
	v_mul_f32_e32 v7, 0xbfb8aa3b, v25
	v_exp_f32_e32 v6, v6
	v_exp_f32_e32 v7, v7
	v_pk_fma_f32 v[2:3], v[20:21], v[8:9], v[2:3]
	v_mul_f32_e32 v8, 0xbfb8aa3b, v26
	v_mul_f32_e32 v9, 0xbfb8aa3b, v27
	s_nop 0
	s_nop 0
	s_nop 0
	v_exp_f32_e32 v8, v8
	v_exp_f32_e32 v9, v9
	v_mov_b32_dpp v10, v4 row_shr:1 row_mask:0xf bank_mask:0xf bound_ctrl:1
	v_mov_b32_dpp v11, v4 row_shr:2 row_mask:0xf bank_mask:0xf bound_ctrl:1
	v_mov_b32_dpp v12, v218 row_shl:1 row_mask:0xf bank_mask:0xf bound_ctrl:1
	v_cndmask_b32_e64 v10, v10, v12, s[6:7]
	v_cndmask_b32_e64 v12, v11, v218, s[4:5]
	s_nop 0
	s_nop 0
	v_add_f32_e32 v6, 1.0, v6
	v_add_f32_e32 v7, 1.0, v7
	v_mov_b32_dpp v11, v5 row_shr:1 row_mask:0xf bank_mask:0xf bound_ctrl:1
	s_nop 0
	v_mov_b32_dpp v14, v219 row_shl:1 row_mask:0xf bank_mask:0xf bound_ctrl:1
	v_rcp_f32_e32 v6, v6
	v_rcp_f32_e32 v7, v7
	v_mov_b32_dpp v13, v5 row_shr:2 row_mask:0xf bank_mask:0xf bound_ctrl:1
	v_cndmask_b32_e64 v11, v11, v14, s[6:7]
	v_pk_fma_f32 v[4:5], v[4:5], v[46:47], v[50:51]
	v_add_f32_e32 v8, 1.0, v8
	v_add_f32_e32 v9, 1.0, v9
	v_cndmask_b32_e64 v13, v13, v219, s[4:5]
	v_pk_fma_f32 v[4:5], v[34:35], v[10:11], v[4:5]
	v_rcp_f32_e32 v8, v8
	v_rcp_f32_e32 v9, v9
	v_pk_fma_f32 v[4:5], v[22:23], v[12:13], v[4:5]
	v_pk_mul_f32 v[6:7], v[24:25], v[6:7]
	s_nop 0
	v_pk_mul_f32 v[2:3], v[6:7], v[2:3]
	s_nop 0
	v_cvt_pk_bf16_f32 v54, v2, v3
	v_pk_mul_f32 v[2:3], v[26:27], v[8:9]
	s_nop 0
	v_pk_mul_f32 v[2:3], v[2:3], v[4:5]
	s_nop 0
	v_cvt_pk_bf16_f32 v55, v2, v3
	v_add_co_u32_e32 v2, vcc, 0xf2000, v114
	s_nop 1
	v_addc_co_u32_e32 v3, vcc, 0, v115, vcc
	global_store_dwordx4 v[2:3], v[54:57], off
	s_waitcnt vmcnt(0)
	s_barrier
